# GEMM K-loops: staging of As[0][0]@t+2 moved from SP2(t) to head of SP1(t+1) (DMAs per segment 2,6,2,6 -> 2,4,4,6), SP2(t) wait vmcnt(8)->(6); on top of v23
# speedup vs baseline: 1.0039x; 1.0039x over previous
; #define PG8_STAGE(bufoff, gbase, voff) do { _Pragma("unroll") for (int _i = 0; _i < 2; ++_i) \
;         __builtin_amdgcn_global_load_lds((const unsigned*)((const char*)(gbase) + (voff)[_i]), (PG8_LAS unsigned*)(lds + (bufoff) + ldsw + _i * 8192), 16, 0, 0); } while (0)
; #define PG8_LDA(dst, b, h) do { _Pragma("unroll") for (int m = 0; m < 4; ++m) _Pragma("unroll") for (int k = 0; k < 2; ++k) dst[m][k] = *(const PG8_LAS bf16x8*)(lds + PG8_SA(b, h) + aoff + m * 2048 + k * 1024); } while (0)
; #define PG8_LDB(dst, b, h) do { _Pragma("unroll") for (int n = 0; n < 2; ++n) _Pragma("unroll") for (int k = 0; k < 2; ++k) dst[n][k] = *(const PG8_LAS bf16x8*)(lds + PG8_SB(b, h) + boff + n * 2048 + k * 1024); } while (0)
; #define PG8_MMA(ai, bj, At, Bt) do { __builtin_amdgcn_s_setprio(1); _Pragma("unroll") for (int m = 0; m < 4; ++m) _Pragma("unroll") for (int n = 0; n < 2; ++n) _Pragma("unroll") for (int k = 0; k < 2; ++k) \
;         acc[ai][bj][m][n] = __builtin_amdgcn_mfma_f32_16x16x32_bf16(Bt[n][k], At[m][k], acc[ai][bj][m][n], 0, 0, 0); __builtin_amdgcn_s_setprio(0); } while (0)
; #define PG8_WAIT_V(n) asm volatile("s_waitcnt vmcnt(" #n ")" ::: "memory")
; #define PG8_WAIT_L(n) asm volatile("s_waitcnt lgkmcnt(" #n ")" ::: "memory")
; #define PG8_BAR __builtin_amdgcn_s_barrier()
; #define PG8_SCHED __builtin_amdgcn_sched_barrier(0)
; template <class Epi, class Sched, bool ALIGN_EPI = false, bool SP2 = false>
; __device__ __forceinline__ void gemm_phase(PG8_LAS unsigned char* lds, const Gemm g, const Sched& S, const Epi& E) {
;     ...
;             const bool last = (t == nt - 2);
;             const char* a1 = cA + (size_t)(t + 1) * kstep;
;             const char* a2 = last ? nA : cA + (size_t)(t + 2) * kstep; const char* b2 = last ? nB : cB + (size_t)(t + 2) * kstep;
;             const char* a3 = a2 + kstep; const char* b3 = b2 + kstep;
;             if (last && has_next) S.a_ready(nxt);
;             if constexpr (SP2) {
;             PG8_LDB(B0, 0, 0); PG8_LDB(B1, 0, 1); PG8_SCHED; PG8_LDA(At, 0, 0); PG8_STAGE(PG8_SA(1, 1), a1 + hstep, voffA);
;             PG8_WAIT_V(8); PG8_WAIT_L(0); PG8_BAR; PG8_MMA(0, 0, At, B0); PG8_MMA(0, 1, At, B1); PG8_BAR; PG8_SCHED;
;             PG8_LDA(At, 0, 1); PG8_STAGE(PG8_SB(0, 0), b2, voffB); PG8_STAGE(PG8_SB(0, 1), b2 + hstep, voffB); PG8_STAGE(PG8_SA(0, 0), a2, voffA);
.LBB0_264:
	s_add_u32 s19, s80, 0xfffc0080
	s_addc_u32 s82, s81, -1
	s_add_i32 vcc_lo, 0, 0x10000
	s_cmp_eq_u32 s79, 12
	s_cselect_b32 s85, s7, s82
	s_cselect_b32 s84, s16, s19
	s_cselect_b32 s83, s17, s73
	s_cselect_b32 s82, s18, s71
	s_add_i32 s19, 0, 0x14000
	v_add_u32_e32 v140, vcc_lo, v201
	v_add_u32_e32 v156, s19, v201
	ds_read_b128 v[128:131], v140
	ds_read_b128 v[132:135], v140 offset:1024
	ds_read_b128 v[136:139], v140 offset:2048
	ds_read_b128 v[140:143], v140 offset:3072
	ds_read_b128 v[144:147], v156
	ds_read_b128 v[148:151], v156 offset:1024
	ds_read_b128 v[152:155], v156 offset:2048
	ds_read_b128 v[156:159], v156 offset:3072
	v_lshl_add_u64 v[198:199], s[80:81], 0, v[182:183]
	s_add_i32 m0, s93, 0xc000
	ds_read_b128 v[186:189], v209
	ds_read_b128 v[190:193], v209 offset:1024
	ds_read_b128 v[194:197], v209 offset:2048
	ds_read_b128 v[210:213], v209 offset:3072
	ds_read_b128 v[214:217], v209 offset:4096
	ds_read_b128 v[230:233], v209 offset:5120
	ds_read_b128 v[234:237], v209 offset:6144
	ds_read_b128 v[238:241], v209 offset:7168
	global_load_lds_dwordx4 v[198:199], off
	v_lshl_add_u64 v[198:199], s[80:81], 0, v[184:185]
	s_add_i32 m0, s93, 0xe000
	s_nop 0
	global_load_lds_dwordx4 v[198:199], off
	s_waitcnt vmcnt(8)
	s_waitcnt lgkmcnt(0)
	s_barrier
	s_setprio 1
	s_waitcnt lgkmcnt(0)
	v_mfma_f32_16x16x32_bf16 v[124:127], v[128:131], v[186:189], v[124:127]
	v_mfma_f32_16x16x32_bf16 v[120:123], v[136:139], v[186:189], v[120:123]
	v_mfma_f32_16x16x32_bf16 v[108:111], v[128:131], v[194:197], v[108:111]
	v_mfma_f32_16x16x32_bf16 v[104:107], v[136:139], v[194:197], v[104:107]
	v_mfma_f32_16x16x32_bf16 v[92:95], v[128:131], v[214:217], v[92:95]
	v_mfma_f32_16x16x32_bf16 v[88:91], v[136:139], v[214:217], v[88:91]
	v_mfma_f32_16x16x32_bf16 v[76:79], v[128:131], v[234:237], v[76:79]
	v_mfma_f32_16x16x32_bf16 v[72:75], v[136:139], v[234:237], v[72:75]
	v_mfma_f32_16x16x32_bf16 v[124:127], v[132:135], v[190:193], v[124:127]
	v_mfma_f32_16x16x32_bf16 v[120:123], v[140:143], v[190:193], v[120:123]
	v_mfma_f32_16x16x32_bf16 v[108:111], v[132:135], v[210:213], v[108:111]
	v_mfma_f32_16x16x32_bf16 v[104:107], v[140:143], v[210:213], v[104:107]
	v_mfma_f32_16x16x32_bf16 v[92:95], v[132:135], v[230:233], v[92:95]
	v_mfma_f32_16x16x32_bf16 v[88:91], v[140:143], v[230:233], v[88:91]
	v_mfma_f32_16x16x32_bf16 v[76:79], v[132:135], v[238:241], v[76:79]
	v_mfma_f32_16x16x32_bf16 v[72:75], v[140:143], v[238:241], v[72:75]
	s_setprio 0
	s_setprio 1
	v_mfma_f32_16x16x32_bf16 v[116:119], v[144:147], v[186:189], v[116:119]
	v_mfma_f32_16x16x32_bf16 v[112:115], v[152:155], v[186:189], v[112:115]
	v_mfma_f32_16x16x32_bf16 v[100:103], v[144:147], v[194:197], v[100:103]
	v_mfma_f32_16x16x32_bf16 v[96:99], v[152:155], v[194:197], v[96:99]
	v_mfma_f32_16x16x32_bf16 v[84:87], v[144:147], v[214:217], v[84:87]
	v_mfma_f32_16x16x32_bf16 v[80:83], v[152:155], v[214:217], v[80:83]
	v_mfma_f32_16x16x32_bf16 v[68:71], v[144:147], v[234:237], v[68:71]
	v_mfma_f32_16x16x32_bf16 v[64:67], v[152:155], v[234:237], v[64:67]
	v_mfma_f32_16x16x32_bf16 v[116:119], v[148:151], v[190:193], v[116:119]
	v_mfma_f32_16x16x32_bf16 v[112:115], v[156:159], v[190:193], v[112:115]
	v_mfma_f32_16x16x32_bf16 v[100:103], v[148:151], v[210:213], v[100:103]
	v_mfma_f32_16x16x32_bf16 v[96:99], v[156:159], v[210:213], v[96:99]
	v_mfma_f32_16x16x32_bf16 v[84:87], v[148:151], v[230:233], v[84:87]
	v_mfma_f32_16x16x32_bf16 v[80:83], v[156:159], v[230:233], v[80:83]
	v_mfma_f32_16x16x32_bf16 v[68:71], v[148:151], v[238:241], v[68:71]
	v_mfma_f32_16x16x32_bf16 v[64:67], v[156:159], v[238:241], v[64:67]
	s_setprio 0
	s_barrier
	s_add_i32 vcc_lo, vcc_lo, s92
	v_lshl_add_u64 v[198:199], s[82:83], 0, v[170:171]
	s_mov_b32 m0, vcc_lo
	ds_read_b128 v[186:189], v209 offset:16384
	ds_read_b128 v[190:193], v209 offset:17408
	ds_read_b128 v[194:197], v209 offset:18432
	ds_read_b128 v[210:213], v209 offset:19456
	ds_read_b128 v[214:217], v209 offset:20480
	ds_read_b128 v[230:233], v209 offset:21504
	ds_read_b128 v[234:237], v209 offset:22528
	ds_read_b128 v[238:241], v209 offset:23552
	global_load_lds_dwordx4 v[198:199], off
	s_add_i32 m0, vcc_lo, 0x2000
	s_add_u32 vcc_lo, s82, 0x40000
	v_lshl_add_u64 v[224:225], s[82:83], 0, v[174:175]
	s_addc_u32 vcc_hi, s83, 0
	s_add_i32 s19, s19, s92
	global_load_lds_dwordx4 v[224:225], off
	v_lshl_add_u64 v[226:227], vcc, 0, v[170:171]
	s_mov_b32 m0, s19
	v_lshl_add_u64 v[242:243], s[84:85], 0, v[172:173]
	global_load_lds_dwordx4 v[226:227], off
	v_lshl_add_u64 v[226:227], vcc, 0, v[174:175]
	s_add_i32 m0, s19, 0x2000
	s_nop 0
	global_load_lds_dwordx4 v[226:227], off
	v_lshl_add_u64 v[226:227], s[84:85], 0, v[168:169]
	s_waitcnt vmcnt(6)
	s_waitcnt lgkmcnt(0)
	s_barrier
; #define PG8_STAGE(bufoff, gbase, voff) do { _Pragma("unroll") for (int _i = 0; _i < 2; ++_i) \
;         __builtin_amdgcn_global_load_lds((const unsigned*)((const char*)(gbase) + (voff)[_i]), (PG8_LAS unsigned*)(lds + (bufoff) + ldsw + _i * 8192), 16, 0, 0); } while (0)
; #define PG8_LDA(dst, b, h) do { _Pragma("unroll") for (int m = 0; m < 4; ++m) _Pragma("unroll") for (int k = 0; k < 2; ++k) dst[m][k] = *(const PG8_LAS bf16x8*)(lds + PG8_SA(b, h) + aoff + m * 2048 + k * 1024); } while (0)
; #define PG8_LDB(dst, b, h) do { _Pragma("unroll") for (int n = 0; n < 2; ++n) _Pragma("unroll") for (int k = 0; k < 2; ++k) dst[n][k] = *(const PG8_LAS bf16x8*)(lds + PG8_SB(b, h) + boff + n * 2048 + k * 1024); } while (0)
; #define PG8_MMA(ai, bj, At, Bt) do { __builtin_amdgcn_s_setprio(1); _Pragma("unroll") for (int m = 0; m < 4; ++m) _Pragma("unroll") for (int n = 0; n < 2; ++n) _Pragma("unroll") for (int k = 0; k < 2; ++k) \
;         acc[ai][bj][m][n] = __builtin_amdgcn_mfma_f32_16x16x32_bf16(Bt[n][k], At[m][k], acc[ai][bj][m][n], 0, 0, 0); __builtin_amdgcn_s_setprio(0); } while (0)
; #define PG8_WAIT_V(n) asm volatile("s_waitcnt vmcnt(" #n ")" ::: "memory")
; #define PG8_WAIT_L(n) asm volatile("s_waitcnt lgkmcnt(" #n ")" ::: "memory")
; #define PG8_BAR __builtin_amdgcn_s_barrier()
; #define PG8_SCHED __builtin_amdgcn_sched_barrier(0)
; template <class Epi, class Sched, bool ALIGN_EPI = false, bool SP2 = false>
; __device__ __forceinline__ void gemm_phase(PG8_LAS unsigned char* lds, const Gemm g, const Sched& S, const Epi& E) {
;     ...
;             PG8_WAIT_V(8); PG8_WAIT_L(0); PG8_BAR; PG8_MMA(1, 0, At, B0); PG8_MMA(1, 1, At, B1); PG8_BAR; PG8_SCHED;
;             PG8_LDB(B0, 1, 0); PG8_LDB(B1, 1, 1); PG8_SCHED; PG8_LDA(At, 1, 0); PG8_STAGE(PG8_SA(0, 1), a2 + hstep, voffA);
;             PG8_WAIT_V(8); PG8_WAIT_L(0); PG8_BAR; PG8_MMA(0, 0, At, B0); PG8_MMA(0, 1, At, B1); PG8_BAR; PG8_SCHED;
;             PG8_LDA(At, 1, 1); PG8_STAGE(PG8_SB(1, 0), b3, voffB); PG8_STAGE(PG8_SB(1, 1), b3 + hstep, voffB); PG8_STAGE(PG8_SA(1, 0), a3, voffA);
	s_setprio 1
	s_waitcnt lgkmcnt(0)
	v_mfma_f32_16x16x32_bf16 v[60:63], v[128:131], v[186:189], v[60:63]
	v_mfma_f32_16x16x32_bf16 v[56:59], v[136:139], v[186:189], v[56:59]
	v_mfma_f32_16x16x32_bf16 v[44:47], v[128:131], v[194:197], v[44:47]
	v_mfma_f32_16x16x32_bf16 v[40:43], v[136:139], v[194:197], v[40:43]
	v_mfma_f32_16x16x32_bf16 v[28:31], v[128:131], v[214:217], v[28:31]
	v_mfma_f32_16x16x32_bf16 v[24:27], v[136:139], v[214:217], v[24:27]
	v_mfma_f32_16x16x32_bf16 v[12:15], v[128:131], v[234:237], v[12:15]
	v_mfma_f32_16x16x32_bf16 v[8:11], v[136:139], v[234:237], v[8:11]
	v_mfma_f32_16x16x32_bf16 v[60:63], v[132:135], v[190:193], v[60:63]
	v_mfma_f32_16x16x32_bf16 v[56:59], v[140:143], v[190:193], v[56:59]
	v_mfma_f32_16x16x32_bf16 v[44:47], v[132:135], v[210:213], v[44:47]
	v_mfma_f32_16x16x32_bf16 v[40:43], v[140:143], v[210:213], v[40:43]
	v_mfma_f32_16x16x32_bf16 v[28:31], v[132:135], v[230:233], v[28:31]
	v_mfma_f32_16x16x32_bf16 v[24:27], v[140:143], v[230:233], v[24:27]
	v_mfma_f32_16x16x32_bf16 v[12:15], v[132:135], v[238:241], v[12:15]
	v_mfma_f32_16x16x32_bf16 v[8:11], v[140:143], v[238:241], v[8:11]
	s_setprio 0
	s_setprio 1
	v_mfma_f32_16x16x32_bf16 v[52:55], v[144:147], v[186:189], v[52:55]
	v_mfma_f32_16x16x32_bf16 v[48:51], v[152:155], v[186:189], v[48:51]
	v_mfma_f32_16x16x32_bf16 v[36:39], v[144:147], v[194:197], v[36:39]
	v_mfma_f32_16x16x32_bf16 v[32:35], v[152:155], v[194:197], v[32:35]
	v_mfma_f32_16x16x32_bf16 v[20:23], v[144:147], v[214:217], v[20:23]
	v_mfma_f32_16x16x32_bf16 v[16:19], v[152:155], v[214:217], v[16:19]
	v_mfma_f32_16x16x32_bf16 v[4:7], v[144:147], v[234:237], v[4:7]
	v_mfma_f32_16x16x32_bf16 v[0:3], v[152:155], v[234:237], v[0:3]
	v_mfma_f32_16x16x32_bf16 v[52:55], v[148:151], v[190:193], v[52:55]
	v_mfma_f32_16x16x32_bf16 v[48:51], v[156:159], v[190:193], v[48:51]
	v_mfma_f32_16x16x32_bf16 v[36:39], v[148:151], v[210:213], v[36:39]
	v_mfma_f32_16x16x32_bf16 v[32:35], v[156:159], v[210:213], v[32:35]
	v_mfma_f32_16x16x32_bf16 v[20:23], v[148:151], v[230:233], v[20:23]
	v_mfma_f32_16x16x32_bf16 v[16:19], v[156:159], v[230:233], v[16:19]
	v_mfma_f32_16x16x32_bf16 v[4:7], v[148:151], v[238:241], v[4:7]
	v_mfma_f32_16x16x32_bf16 v[0:3], v[156:159], v[238:241], v[0:3]
	s_setprio 0
	s_barrier
	s_add_i32 s19, 0, 0x18000
	s_add_i32 vcc_lo, 0, 0x1c000
	v_add_u32_e32 v140, s19, v201
	v_add_u32_e32 v156, vcc_lo, v201
	ds_read_b128 v[128:131], v140
	ds_read_b128 v[132:135], v140 offset:1024
	ds_read_b128 v[136:139], v140 offset:2048
	ds_read_b128 v[140:143], v140 offset:3072
	ds_read_b128 v[144:147], v156
	ds_read_b128 v[148:151], v156 offset:1024
	ds_read_b128 v[152:155], v156 offset:2048
	ds_read_b128 v[156:159], v156 offset:3072
	s_add_u32 s84, s84, 0x40000
	s_addc_u32 s85, s85, 0
	s_mov_b32 m0, s93
	s_nop 0
	global_load_lds_dwordx4 v[226:227], off
	s_mov_b32 m0, s94
	s_nop 0
	global_load_lds_dwordx4 v[242:243], off
	s_mov_b32 m0, s95
	v_lshl_add_u64 v[244:245], s[84:85], 0, v[168:169]
	ds_read_b128 v[186:189], v209 offset:32768
	ds_read_b128 v[190:193], v209 offset:33792
	ds_read_b128 v[194:197], v209 offset:34816
	ds_read_b128 v[210:213], v209 offset:35840
	ds_read_b128 v[214:217], v209 offset:36864
	ds_read_b128 v[230:233], v209 offset:37888
	ds_read_b128 v[234:237], v209 offset:38912
	ds_read_b128 v[238:241], v209 offset:39936
	global_load_lds_dwordx4 v[244:245], off
	v_lshl_add_u64 v[244:245], s[84:85], 0, v[172:173]
	s_mov_b32 m0, s96
	s_nop 0
	global_load_lds_dwordx4 v[244:245], off
	s_waitcnt vmcnt(8)
	s_waitcnt lgkmcnt(0)
	s_barrier
	s_setprio 1
	s_waitcnt lgkmcnt(0)
	v_mfma_f32_16x16x32_bf16 v[124:127], v[128:131], v[186:189], v[124:127]
	v_mfma_f32_16x16x32_bf16 v[120:123], v[136:139], v[186:189], v[120:123]
	v_mfma_f32_16x16x32_bf16 v[108:111], v[128:131], v[194:197], v[108:111]
	v_mfma_f32_16x16x32_bf16 v[104:107], v[136:139], v[194:197], v[104:107]
	v_mfma_f32_16x16x32_bf16 v[92:95], v[128:131], v[214:217], v[92:95]
	v_mfma_f32_16x16x32_bf16 v[88:91], v[136:139], v[214:217], v[88:91]
	v_mfma_f32_16x16x32_bf16 v[76:79], v[128:131], v[234:237], v[76:79]
	v_mfma_f32_16x16x32_bf16 v[72:75], v[136:139], v[234:237], v[72:75]
	v_mfma_f32_16x16x32_bf16 v[124:127], v[132:135], v[190:193], v[124:127]
	v_mfma_f32_16x16x32_bf16 v[120:123], v[140:143], v[190:193], v[120:123]
	v_mfma_f32_16x16x32_bf16 v[108:111], v[132:135], v[210:213], v[108:111]
	v_mfma_f32_16x16x32_bf16 v[104:107], v[140:143], v[210:213], v[104:107]
	v_mfma_f32_16x16x32_bf16 v[92:95], v[132:135], v[230:233], v[92:95]
	v_mfma_f32_16x16x32_bf16 v[88:91], v[140:143], v[230:233], v[88:91]
	v_mfma_f32_16x16x32_bf16 v[76:79], v[132:135], v[238:241], v[76:79]
	v_mfma_f32_16x16x32_bf16 v[72:75], v[140:143], v[238:241], v[72:75]
	s_setprio 0
	s_setprio 1
	v_mfma_f32_16x16x32_bf16 v[116:119], v[144:147], v[186:189], v[116:119]
	v_mfma_f32_16x16x32_bf16 v[112:115], v[152:155], v[186:189], v[112:115]
	v_mfma_f32_16x16x32_bf16 v[100:103], v[144:147], v[194:197], v[100:103]
	v_mfma_f32_16x16x32_bf16 v[96:99], v[152:155], v[194:197], v[96:99]
	v_mfma_f32_16x16x32_bf16 v[84:87], v[144:147], v[214:217], v[84:87]
	v_mfma_f32_16x16x32_bf16 v[80:83], v[152:155], v[214:217], v[80:83]
	v_mfma_f32_16x16x32_bf16 v[68:71], v[144:147], v[234:237], v[68:71]
	v_mfma_f32_16x16x32_bf16 v[64:67], v[152:155], v[234:237], v[64:67]
	v_mfma_f32_16x16x32_bf16 v[116:119], v[148:151], v[190:193], v[116:119]
	v_mfma_f32_16x16x32_bf16 v[112:115], v[156:159], v[190:193], v[112:115]
	v_mfma_f32_16x16x32_bf16 v[100:103], v[148:151], v[210:213], v[100:103]
	v_mfma_f32_16x16x32_bf16 v[96:99], v[156:159], v[210:213], v[96:99]
	v_mfma_f32_16x16x32_bf16 v[84:87], v[148:151], v[230:233], v[84:87]
	v_mfma_f32_16x16x32_bf16 v[80:83], v[156:159], v[230:233], v[80:83]
	v_mfma_f32_16x16x32_bf16 v[68:71], v[148:151], v[238:241], v[68:71]
	v_mfma_f32_16x16x32_bf16 v[64:67], v[156:159], v[238:241], v[64:67]
	s_setprio 0
	s_barrier
; #define PG8_STAGE(bufoff, gbase, voff) do { _Pragma("unroll") for (int _i = 0; _i < 2; ++_i) \
;         __builtin_amdgcn_global_load_lds((const unsigned*)((const char*)(gbase) + (voff)[_i]), (PG8_LAS unsigned*)(lds + (bufoff) + ldsw + _i * 8192), 16, 0, 0); } while (0)
; #define PG8_LDA(dst, b, h) do { _Pragma("unroll") for (int m = 0; m < 4; ++m) _Pragma("unroll") for (int k = 0; k < 2; ++k) dst[m][k] = *(const PG8_LAS bf16x8*)(lds + PG8_SA(b, h) + aoff + m * 2048 + k * 1024); } while (0)
; #define PG8_MMA(ai, bj, At, Bt) do { __builtin_amdgcn_s_setprio(1); _Pragma("unroll") for (int m = 0; m < 4; ++m) _Pragma("unroll") for (int n = 0; n < 2; ++n) _Pragma("unroll") for (int k = 0; k < 2; ++k) \
;         acc[ai][bj][m][n] = __builtin_amdgcn_mfma_f32_16x16x32_bf16(Bt[n][k], At[m][k], acc[ai][bj][m][n], 0, 0, 0); __builtin_amdgcn_s_setprio(0); } while (0)
; #define PG8_WAIT_V(n) asm volatile("s_waitcnt vmcnt(" #n ")" ::: "memory")
; #define PG8_WAIT_L(n) asm volatile("s_waitcnt lgkmcnt(" #n ")" ::: "memory")
; #define PG8_BAR __builtin_amdgcn_s_barrier()
; #define PG8_SCHED __builtin_amdgcn_sched_barrier(0)
; template <class Epi, class Sched, bool ALIGN_EPI = false, bool SP2 = false>
; __device__ __forceinline__ void gemm_phase(PG8_LAS unsigned char* lds, const Gemm g, const Sched& S, const Epi& E) {
;     ...
;             PG8_LDA(At, 1, 1); PG8_STAGE(PG8_SB(1, 0), b3, voffB); PG8_STAGE(PG8_SB(1, 1), b3 + hstep, voffB); PG8_STAGE(PG8_SA(1, 0), a3, voffA);
;             PG8_WAIT_V(8); PG8_WAIT_L(0); PG8_BAR; PG8_MMA(1, 0, At, B0); PG8_MMA(1, 1, At, B1); PG8_BAR; PG8_SCHED;
	s_add_i32 s19, s19, s92
	v_lshl_add_u64 v[198:199], v[198:199], 0, s[22:23]
	s_mov_b32 m0, s19
	ds_read_b128 v[186:189], v209 offset:49152
	ds_read_b128 v[190:193], v209 offset:50176
	ds_read_b128 v[194:197], v209 offset:51200
	ds_read_b128 v[210:213], v209 offset:52224
	ds_read_b128 v[214:217], v209 offset:53248
	ds_read_b128 v[230:233], v209 offset:54272
	ds_read_b128 v[234:237], v209 offset:55296
	ds_read_b128 v[238:241], v209 offset:56320
	global_load_lds_dwordx4 v[198:199], off
	s_add_i32 m0, s19, 0x2000
	s_add_u32 s82, s82, 0x40080
	v_lshl_add_u64 v[198:199], v[224:225], 0, s[22:23]
	s_addc_u32 s83, s83, 0
	s_add_i32 s19, vcc_lo, s92
	global_load_lds_dwordx4 v[198:199], off
	v_lshl_add_u64 v[198:199], s[82:83], 0, v[170:171]
	s_mov_b32 m0, s19
	s_nop 0
	global_load_lds_dwordx4 v[198:199], off
	v_lshl_add_u64 v[198:199], s[82:83], 0, v[174:175]
	s_add_i32 m0, s19, 0x2000
	s_nop 0
	global_load_lds_dwordx4 v[198:199], off
	v_lshl_add_u64 v[198:199], v[226:227], 0, s[22:23]
	s_mov_b32 m0, s97
	s_nop 0
	global_load_lds_dwordx4 v[198:199], off
	v_lshl_add_u64 v[198:199], v[242:243], 0, s[22:23]
	s_mov_b32 m0, s61
	s_nop 0
	global_load_lds_dwordx4 v[198:199], off
	s_waitcnt vmcnt(8)
	s_waitcnt lgkmcnt(0)
	s_barrier
	s_setprio 1
	s_waitcnt lgkmcnt(0)
	v_mfma_f32_16x16x32_bf16 v[60:63], v[128:131], v[186:189], v[60:63]
	v_mfma_f32_16x16x32_bf16 v[56:59], v[136:139], v[186:189], v[56:59]
	v_mfma_f32_16x16x32_bf16 v[44:47], v[128:131], v[194:197], v[44:47]
	v_mfma_f32_16x16x32_bf16 v[40:43], v[136:139], v[194:197], v[40:43]
	v_mfma_f32_16x16x32_bf16 v[28:31], v[128:131], v[214:217], v[28:31]
	v_mfma_f32_16x16x32_bf16 v[24:27], v[136:139], v[214:217], v[24:27]
	v_mfma_f32_16x16x32_bf16 v[12:15], v[128:131], v[234:237], v[12:15]
	v_mfma_f32_16x16x32_bf16 v[8:11], v[136:139], v[234:237], v[8:11]
	v_mfma_f32_16x16x32_bf16 v[60:63], v[132:135], v[190:193], v[60:63]
	v_mfma_f32_16x16x32_bf16 v[56:59], v[140:143], v[190:193], v[56:59]
	v_mfma_f32_16x16x32_bf16 v[44:47], v[132:135], v[210:213], v[44:47]
	v_mfma_f32_16x16x32_bf16 v[40:43], v[140:143], v[210:213], v[40:43]
	v_mfma_f32_16x16x32_bf16 v[28:31], v[132:135], v[230:233], v[28:31]
	v_mfma_f32_16x16x32_bf16 v[24:27], v[140:143], v[230:233], v[24:27]
	v_mfma_f32_16x16x32_bf16 v[12:15], v[132:135], v[238:241], v[12:15]
	v_mfma_f32_16x16x32_bf16 v[8:11], v[140:143], v[238:241], v[8:11]
	s_setprio 0
	s_setprio 1
	v_mfma_f32_16x16x32_bf16 v[52:55], v[144:147], v[186:189], v[52:55]
	v_mfma_f32_16x16x32_bf16 v[48:51], v[152:155], v[186:189], v[48:51]
	v_mfma_f32_16x16x32_bf16 v[36:39], v[144:147], v[194:197], v[36:39]
	v_mfma_f32_16x16x32_bf16 v[32:35], v[152:155], v[194:197], v[32:35]
	v_mfma_f32_16x16x32_bf16 v[20:23], v[144:147], v[214:217], v[20:23]
	v_mfma_f32_16x16x32_bf16 v[16:19], v[152:155], v[214:217], v[16:19]
	v_mfma_f32_16x16x32_bf16 v[4:7], v[144:147], v[234:237], v[4:7]
	v_mfma_f32_16x16x32_bf16 v[0:3], v[152:155], v[234:237], v[0:3]
	v_mfma_f32_16x16x32_bf16 v[52:55], v[148:151], v[190:193], v[52:55]
	v_mfma_f32_16x16x32_bf16 v[48:51], v[156:159], v[190:193], v[48:51]
	v_mfma_f32_16x16x32_bf16 v[36:39], v[148:151], v[210:213], v[36:39]
	v_mfma_f32_16x16x32_bf16 v[32:35], v[156:159], v[210:213], v[32:35]
	v_mfma_f32_16x16x32_bf16 v[20:23], v[148:151], v[230:233], v[20:23]
	v_mfma_f32_16x16x32_bf16 v[16:19], v[156:159], v[230:233], v[16:19]
	v_mfma_f32_16x16x32_bf16 v[4:7], v[148:151], v[238:241], v[4:7]
	v_mfma_f32_16x16x32_bf16 v[0:3], v[156:159], v[238:241], v[0:3]
	s_setprio 0
	s_barrier
	s_add_i32 s79, s79, 2
	s_add_u32 s80, s80, 0x100
	s_addc_u32 s81, s81, 0
	s_add_u32 s71, s71, 0x100
	s_addc_u32 s73, s73, 0
	s_cmp_gt_u32 s79, 13
	s_cbranch_scc0 .LBB0_264
	s_and_b64 vcc, exec, s[68:69]
	s_cbranch_vccz .LBB0_267
	s_barrier

; #define PG8_STAGE(bufoff, gbase, voff) do { _Pragma("unroll") for (int _i = 0; _i < 2; ++_i) \
;         __builtin_amdgcn_global_load_lds((const unsigned*)((const char*)(gbase) + (voff)[_i]), (PG8_LAS unsigned*)(lds + (bufoff) + ldsw + _i * 8192), 16, 0, 0); } while (0)
; #define PG8_LDA(dst, b, h) do { _Pragma("unroll") for (int m = 0; m < 4; ++m) _Pragma("unroll") for (int k = 0; k < 2; ++k) dst[m][k] = *(const PG8_LAS bf16x8*)(lds + PG8_SA(b, h) + aoff + m * 2048 + k * 1024); } while (0)
; #define PG8_LDB(dst, b, h) do { _Pragma("unroll") for (int n = 0; n < 2; ++n) _Pragma("unroll") for (int k = 0; k < 2; ++k) dst[n][k] = *(const PG8_LAS bf16x8*)(lds + PG8_SB(b, h) + boff + n * 2048 + k * 1024); } while (0)
; #define PG8_MMA(ai, bj, At, Bt) do { __builtin_amdgcn_s_setprio(1); _Pragma("unroll") for (int m = 0; m < 4; ++m) _Pragma("unroll") for (int n = 0; n < 2; ++n) _Pragma("unroll") for (int k = 0; k < 2; ++k) \
;         acc[ai][bj][m][n] = __builtin_amdgcn_mfma_f32_16x16x32_bf16(Bt[n][k], At[m][k], acc[ai][bj][m][n], 0, 0, 0); __builtin_amdgcn_s_setprio(0); } while (0)
; #define PG8_WAIT_V(n) asm volatile("s_waitcnt vmcnt(" #n ")" ::: "memory")
; #define PG8_WAIT_L(n) asm volatile("s_waitcnt lgkmcnt(" #n ")" ::: "memory")
; #define PG8_BAR __builtin_amdgcn_s_barrier()
; #define PG8_SCHED __builtin_amdgcn_sched_barrier(0)
; template <class Epi, class Sched, bool ALIGN_EPI = false, bool SP2 = false>
; __device__ __forceinline__ void gemm_phase(PG8_LAS unsigned char* lds, const Gemm g, const Sched& S, const Epi& E) {
;     ...
;             const bool last = (t == nt - 2);
;             const char* a1 = cA + (size_t)(t + 1) * kstep;
;             const char* a2 = last ? nA : cA + (size_t)(t + 2) * kstep; const char* b2 = last ? nB : cB + (size_t)(t + 2) * kstep;
;             const char* a3 = a2 + kstep; const char* b3 = b2 + kstep;
;             if (last && has_next) S.a_ready(nxt);
;             if constexpr (SP2) {
;             PG8_LDB(B0, 0, 0); PG8_LDB(B1, 0, 1); PG8_SCHED; PG8_LDA(At, 0, 0); PG8_STAGE(PG8_SA(1, 1), a1 + hstep, voffA);
;             PG8_WAIT_V(8); PG8_WAIT_L(0); PG8_BAR; PG8_MMA(0, 0, At, B0); PG8_MMA(0, 1, At, B1); PG8_BAR; PG8_SCHED;
;             PG8_LDA(At, 0, 1); PG8_STAGE(PG8_SB(0, 0), b2, voffB); PG8_STAGE(PG8_SB(0, 1), b2 + hstep, voffB); PG8_STAGE(PG8_SA(0, 0), a2, voffA);
.LBB0_1068:
	s_add_u32 s80, s78, 0x100
	s_addc_u32 s81, s79, 0
	s_add_i32 s44, 0, 0x10000
	s_cmp_eq_u32 s19, 12
	s_cselect_b32 s85, s16, s81
	s_cselect_b32 s84, s17, s80
	s_cselect_b32 s83, s69, vcc_hi
	s_cselect_b32 s82, s71, vcc_lo
	s_add_i32 s34, 0, 0x14000
	v_add_u32_e32 v140, s44, v153
	v_add_u32_e32 v150, s34, v153
	ds_read_b128 v[128:131], v140
	ds_read_b128 v[132:135], v140 offset:1024
	ds_read_b128 v[136:139], v140 offset:2048
	ds_read_b128 v[140:143], v140 offset:3072
	ds_read_b128 v[156:159], v150
	ds_read_b128 v[168:171], v150 offset:1024
	ds_read_b128 v[172:175], v150 offset:2048
	ds_read_b128 v[178:181], v150 offset:3072
	v_lshl_add_u64 v[150:151], s[78:79], 0, v[146:147]
	s_add_i32 m0, s77, 0xc000
	ds_read_b128 v[182:185], v155
	ds_read_b128 v[186:189], v155 offset:1024
	ds_read_b128 v[190:193], v155 offset:2048
	ds_read_b128 v[194:197], v155 offset:3072
	ds_read_b128 v[198:201], v155 offset:4096
	ds_read_b128 v[202:205], v155 offset:5120
	ds_read_b128 v[206:209], v155 offset:6144
	ds_read_b128 v[210:213], v155 offset:7168
	global_load_lds_dwordx4 v[150:151], off
	v_lshl_add_u64 v[150:151], s[78:79], 0, v[148:149]
	s_add_i32 m0, s77, 0xe000
	s_nop 0
	global_load_lds_dwordx4 v[150:151], off
	s_waitcnt vmcnt(8)
	s_waitcnt lgkmcnt(0)
	s_barrier
	s_setprio 1
	s_waitcnt lgkmcnt(0)
	v_mfma_f32_16x16x32_bf16 v[124:127], v[128:131], v[182:185], v[124:127]
	v_mfma_f32_16x16x32_bf16 v[120:123], v[136:139], v[182:185], v[120:123]
	v_mfma_f32_16x16x32_bf16 v[116:119], v[128:131], v[190:193], v[116:119]
	v_mfma_f32_16x16x32_bf16 v[108:111], v[136:139], v[190:193], v[108:111]
	v_mfma_f32_16x16x32_bf16 v[100:103], v[128:131], v[198:201], v[100:103]
	v_mfma_f32_16x16x32_bf16 v[92:95], v[136:139], v[198:201], v[92:95]
	v_mfma_f32_16x16x32_bf16 v[84:87], v[128:131], v[206:209], v[84:87]
	v_mfma_f32_16x16x32_bf16 v[76:79], v[136:139], v[206:209], v[76:79]
	v_mfma_f32_16x16x32_bf16 v[124:127], v[132:135], v[186:189], v[124:127]
	v_mfma_f32_16x16x32_bf16 v[120:123], v[140:143], v[186:189], v[120:123]
	v_mfma_f32_16x16x32_bf16 v[116:119], v[132:135], v[194:197], v[116:119]
	v_mfma_f32_16x16x32_bf16 v[108:111], v[140:143], v[194:197], v[108:111]
	v_mfma_f32_16x16x32_bf16 v[100:103], v[132:135], v[202:205], v[100:103]
	v_mfma_f32_16x16x32_bf16 v[92:95], v[140:143], v[202:205], v[92:95]
	v_mfma_f32_16x16x32_bf16 v[84:87], v[132:135], v[210:213], v[84:87]
	v_mfma_f32_16x16x32_bf16 v[76:79], v[140:143], v[210:213], v[76:79]
	s_setprio 0
	s_setprio 1
	v_mfma_f32_16x16x32_bf16 v[112:115], v[156:159], v[182:185], v[112:115]
	v_mfma_f32_16x16x32_bf16 v[104:107], v[172:175], v[182:185], v[104:107]
	v_mfma_f32_16x16x32_bf16 v[96:99], v[156:159], v[190:193], v[96:99]
	v_mfma_f32_16x16x32_bf16 v[88:91], v[172:175], v[190:193], v[88:91]
	v_mfma_f32_16x16x32_bf16 v[80:83], v[156:159], v[198:201], v[80:83]
	v_mfma_f32_16x16x32_bf16 v[72:75], v[172:175], v[198:201], v[72:75]
	v_mfma_f32_16x16x32_bf16 v[68:71], v[156:159], v[206:209], v[68:71]
	v_mfma_f32_16x16x32_bf16 v[64:67], v[172:175], v[206:209], v[64:67]
	v_mfma_f32_16x16x32_bf16 v[112:115], v[168:171], v[186:189], v[112:115]
	v_mfma_f32_16x16x32_bf16 v[104:107], v[178:181], v[186:189], v[104:107]
	v_mfma_f32_16x16x32_bf16 v[96:99], v[168:171], v[194:197], v[96:99]
	v_mfma_f32_16x16x32_bf16 v[88:91], v[178:181], v[194:197], v[88:91]
	v_mfma_f32_16x16x32_bf16 v[80:83], v[168:171], v[202:205], v[80:83]
	v_mfma_f32_16x16x32_bf16 v[72:75], v[178:181], v[202:205], v[72:75]
	v_mfma_f32_16x16x32_bf16 v[68:71], v[168:171], v[210:213], v[68:71]
	v_mfma_f32_16x16x32_bf16 v[64:67], v[178:181], v[210:213], v[64:67]
	s_setprio 0
	s_barrier
	s_add_i32 s35, s44, s20
	v_lshl_add_u64 v[150:151], s[82:83], 0, v[162:163]
	s_mov_b32 m0, s35
	ds_read_b128 v[182:185], v155 offset:16384
	ds_read_b128 v[186:189], v155 offset:17408
	ds_read_b128 v[190:193], v155 offset:18432
	ds_read_b128 v[194:197], v155 offset:19456
	ds_read_b128 v[198:201], v155 offset:20480
	ds_read_b128 v[202:205], v155 offset:21504
	ds_read_b128 v[206:209], v155 offset:22528
	ds_read_b128 v[210:213], v155 offset:23552
	global_load_lds_dwordx4 v[150:151], off
	s_add_i32 m0, s35, 0x2000
	s_add_u32 s78, s82, 0x40000
	v_lshl_add_u64 v[214:215], s[82:83], 0, v[144:145]
	s_addc_u32 s79, s83, 0
	s_add_i32 s34, s34, s20
	global_load_lds_dwordx4 v[214:215], off
	v_lshl_add_u64 v[216:217], s[78:79], 0, v[162:163]
	s_mov_b32 m0, s34
	v_lshl_add_u64 v[224:225], s[84:85], 0, v[144:145]
	global_load_lds_dwordx4 v[216:217], off
	v_lshl_add_u64 v[216:217], s[78:79], 0, v[144:145]
	s_add_i32 m0, s34, 0x2000
	s_nop 0
	global_load_lds_dwordx4 v[216:217], off
	v_lshl_add_u64 v[216:217], s[84:85], 0, v[162:163]
	s_waitcnt vmcnt(6)
	s_waitcnt lgkmcnt(0)
	s_barrier
; #define PG8_STAGE(bufoff, gbase, voff) do { _Pragma("unroll") for (int _i = 0; _i < 2; ++_i) \
;         __builtin_amdgcn_global_load_lds((const unsigned*)((const char*)(gbase) + (voff)[_i]), (PG8_LAS unsigned*)(lds + (bufoff) + ldsw + _i * 8192), 16, 0, 0); } while (0)
; #define PG8_LDA(dst, b, h) do { _Pragma("unroll") for (int m = 0; m < 4; ++m) _Pragma("unroll") for (int k = 0; k < 2; ++k) dst[m][k] = *(const PG8_LAS bf16x8*)(lds + PG8_SA(b, h) + aoff + m * 2048 + k * 1024); } while (0)
; #define PG8_LDB(dst, b, h) do { _Pragma("unroll") for (int n = 0; n < 2; ++n) _Pragma("unroll") for (int k = 0; k < 2; ++k) dst[n][k] = *(const PG8_LAS bf16x8*)(lds + PG8_SB(b, h) + boff + n * 2048 + k * 1024); } while (0)
; #define PG8_MMA(ai, bj, At, Bt) do { __builtin_amdgcn_s_setprio(1); _Pragma("unroll") for (int m = 0; m < 4; ++m) _Pragma("unroll") for (int n = 0; n < 2; ++n) _Pragma("unroll") for (int k = 0; k < 2; ++k) \
;         acc[ai][bj][m][n] = __builtin_amdgcn_mfma_f32_16x16x32_bf16(Bt[n][k], At[m][k], acc[ai][bj][m][n], 0, 0, 0); __builtin_amdgcn_s_setprio(0); } while (0)
; #define PG8_WAIT_V(n) asm volatile("s_waitcnt vmcnt(" #n ")" ::: "memory")
; #define PG8_WAIT_L(n) asm volatile("s_waitcnt lgkmcnt(" #n ")" ::: "memory")
; #define PG8_BAR __builtin_amdgcn_s_barrier()
; #define PG8_SCHED __builtin_amdgcn_sched_barrier(0)
; template <class Epi, class Sched, bool ALIGN_EPI = false, bool SP2 = false>
; __device__ __forceinline__ void gemm_phase(PG8_LAS unsigned char* lds, const Gemm g, const Sched& S, const Epi& E) {
;     ...
;             PG8_WAIT_V(8); PG8_WAIT_L(0); PG8_BAR; PG8_MMA(1, 0, At, B0); PG8_MMA(1, 1, At, B1); PG8_BAR; PG8_SCHED;
;             PG8_LDB(B0, 1, 0); PG8_LDB(B1, 1, 1); PG8_SCHED; PG8_LDA(At, 1, 0); PG8_STAGE(PG8_SA(0, 1), a2 + hstep, voffA);
;             PG8_WAIT_V(8); PG8_WAIT_L(0); PG8_BAR; PG8_MMA(0, 0, At, B0); PG8_MMA(0, 1, At, B1); PG8_BAR; PG8_SCHED;
;             PG8_LDA(At, 1, 1); PG8_STAGE(PG8_SB(1, 0), b3, voffB); PG8_STAGE(PG8_SB(1, 1), b3 + hstep, voffB); PG8_STAGE(PG8_SA(1, 0), a3, voffA);
	s_setprio 1
	s_waitcnt lgkmcnt(0)
	v_mfma_f32_16x16x32_bf16 v[60:63], v[128:131], v[182:185], v[60:63]
	v_mfma_f32_16x16x32_bf16 v[56:59], v[136:139], v[182:185], v[56:59]
	v_mfma_f32_16x16x32_bf16 v[52:55], v[128:131], v[190:193], v[52:55]
	v_mfma_f32_16x16x32_bf16 v[44:47], v[136:139], v[190:193], v[44:47]
	v_mfma_f32_16x16x32_bf16 v[36:39], v[128:131], v[198:201], v[36:39]
	v_mfma_f32_16x16x32_bf16 v[28:31], v[136:139], v[198:201], v[28:31]
	v_mfma_f32_16x16x32_bf16 v[20:23], v[128:131], v[206:209], v[20:23]
	v_mfma_f32_16x16x32_bf16 v[12:15], v[136:139], v[206:209], v[12:15]
	v_mfma_f32_16x16x32_bf16 v[60:63], v[132:135], v[186:189], v[60:63]
	v_mfma_f32_16x16x32_bf16 v[56:59], v[140:143], v[186:189], v[56:59]
	v_mfma_f32_16x16x32_bf16 v[52:55], v[132:135], v[194:197], v[52:55]
	v_mfma_f32_16x16x32_bf16 v[44:47], v[140:143], v[194:197], v[44:47]
	v_mfma_f32_16x16x32_bf16 v[36:39], v[132:135], v[202:205], v[36:39]
	v_mfma_f32_16x16x32_bf16 v[28:31], v[140:143], v[202:205], v[28:31]
	v_mfma_f32_16x16x32_bf16 v[20:23], v[132:135], v[210:213], v[20:23]
	v_mfma_f32_16x16x32_bf16 v[12:15], v[140:143], v[210:213], v[12:15]
	s_setprio 0
	s_setprio 1
	v_mfma_f32_16x16x32_bf16 v[48:51], v[156:159], v[182:185], v[48:51]
	v_mfma_f32_16x16x32_bf16 v[40:43], v[172:175], v[182:185], v[40:43]
	v_mfma_f32_16x16x32_bf16 v[32:35], v[156:159], v[190:193], v[32:35]
	v_mfma_f32_16x16x32_bf16 v[24:27], v[172:175], v[190:193], v[24:27]
	v_mfma_f32_16x16x32_bf16 v[16:19], v[156:159], v[198:201], v[16:19]
	v_mfma_f32_16x16x32_bf16 v[8:11], v[172:175], v[198:201], v[8:11]
	v_mfma_f32_16x16x32_bf16 v[4:7], v[156:159], v[206:209], v[4:7]
	v_mfma_f32_16x16x32_bf16 v[0:3], v[172:175], v[206:209], v[0:3]
	v_mfma_f32_16x16x32_bf16 v[48:51], v[168:171], v[186:189], v[48:51]
	v_mfma_f32_16x16x32_bf16 v[40:43], v[178:181], v[186:189], v[40:43]
	v_mfma_f32_16x16x32_bf16 v[32:35], v[168:171], v[194:197], v[32:35]
	v_mfma_f32_16x16x32_bf16 v[24:27], v[178:181], v[194:197], v[24:27]
	v_mfma_f32_16x16x32_bf16 v[16:19], v[168:171], v[202:205], v[16:19]
	v_mfma_f32_16x16x32_bf16 v[8:11], v[178:181], v[202:205], v[8:11]
	v_mfma_f32_16x16x32_bf16 v[4:7], v[168:171], v[210:213], v[4:7]
	v_mfma_f32_16x16x32_bf16 v[0:3], v[178:181], v[210:213], v[0:3]
	s_setprio 0
	s_barrier
	s_add_i32 s34, 0, 0x18000
	s_add_i32 s35, 0, 0x1c000
	v_add_u32_e32 v140, s34, v153
	v_add_u32_e32 v176, s35, v153
	ds_read_b128 v[128:131], v140
	ds_read_b128 v[132:135], v140 offset:1024
	ds_read_b128 v[136:139], v140 offset:2048
	ds_read_b128 v[140:143], v140 offset:3072
	ds_read_b128 v[156:159], v176
	ds_read_b128 v[168:171], v176 offset:1024
	ds_read_b128 v[172:175], v176 offset:2048
	ds_read_b128 v[178:181], v176 offset:3072
	s_add_u32 s78, s84, 0x40000
	s_addc_u32 s79, s85, 0
	s_mov_b32 m0, s77
	s_nop 0
	global_load_lds_dwordx4 v[216:217], off
	s_mov_b32 m0, s89
	s_nop 0
	global_load_lds_dwordx4 v[224:225], off
	s_mov_b32 m0, s90
	v_lshl_add_u64 v[226:227], s[78:79], 0, v[162:163]
	ds_read_b128 v[182:185], v155 offset:32768
	ds_read_b128 v[186:189], v155 offset:33792
	ds_read_b128 v[190:193], v155 offset:34816
	ds_read_b128 v[194:197], v155 offset:35840
	ds_read_b128 v[198:201], v155 offset:36864
	ds_read_b128 v[202:205], v155 offset:37888
	ds_read_b128 v[206:209], v155 offset:38912
	ds_read_b128 v[210:213], v155 offset:39936
	global_load_lds_dwordx4 v[226:227], off
	v_lshl_add_u64 v[226:227], s[78:79], 0, v[144:145]
	s_mov_b32 m0, s91
	s_nop 0
	global_load_lds_dwordx4 v[226:227], off
	s_waitcnt vmcnt(8)
	s_waitcnt lgkmcnt(0)
	s_barrier
	s_setprio 1
	s_waitcnt lgkmcnt(0)
	v_mfma_f32_16x16x32_bf16 v[124:127], v[128:131], v[182:185], v[124:127]
	v_mfma_f32_16x16x32_bf16 v[120:123], v[136:139], v[182:185], v[120:123]
	v_mfma_f32_16x16x32_bf16 v[116:119], v[128:131], v[190:193], v[116:119]
	v_mfma_f32_16x16x32_bf16 v[108:111], v[136:139], v[190:193], v[108:111]
	v_mfma_f32_16x16x32_bf16 v[100:103], v[128:131], v[198:201], v[100:103]
	v_mfma_f32_16x16x32_bf16 v[92:95], v[136:139], v[198:201], v[92:95]
	v_mfma_f32_16x16x32_bf16 v[84:87], v[128:131], v[206:209], v[84:87]
	v_mfma_f32_16x16x32_bf16 v[76:79], v[136:139], v[206:209], v[76:79]
	v_mfma_f32_16x16x32_bf16 v[124:127], v[132:135], v[186:189], v[124:127]
	v_mfma_f32_16x16x32_bf16 v[120:123], v[140:143], v[186:189], v[120:123]
	v_mfma_f32_16x16x32_bf16 v[116:119], v[132:135], v[194:197], v[116:119]
	v_mfma_f32_16x16x32_bf16 v[108:111], v[140:143], v[194:197], v[108:111]
	v_mfma_f32_16x16x32_bf16 v[100:103], v[132:135], v[202:205], v[100:103]
	v_mfma_f32_16x16x32_bf16 v[92:95], v[140:143], v[202:205], v[92:95]
	v_mfma_f32_16x16x32_bf16 v[84:87], v[132:135], v[210:213], v[84:87]
	v_mfma_f32_16x16x32_bf16 v[76:79], v[140:143], v[210:213], v[76:79]
	s_setprio 0
	s_setprio 1
	v_mfma_f32_16x16x32_bf16 v[112:115], v[156:159], v[182:185], v[112:115]
	v_mfma_f32_16x16x32_bf16 v[104:107], v[172:175], v[182:185], v[104:107]
	v_mfma_f32_16x16x32_bf16 v[96:99], v[156:159], v[190:193], v[96:99]
	v_mfma_f32_16x16x32_bf16 v[88:91], v[172:175], v[190:193], v[88:91]
	v_mfma_f32_16x16x32_bf16 v[80:83], v[156:159], v[198:201], v[80:83]
	v_mfma_f32_16x16x32_bf16 v[72:75], v[172:175], v[198:201], v[72:75]
	v_mfma_f32_16x16x32_bf16 v[68:71], v[156:159], v[206:209], v[68:71]
	v_mfma_f32_16x16x32_bf16 v[64:67], v[172:175], v[206:209], v[64:67]
	v_mfma_f32_16x16x32_bf16 v[112:115], v[168:171], v[186:189], v[112:115]
	v_mfma_f32_16x16x32_bf16 v[104:107], v[178:181], v[186:189], v[104:107]
	v_mfma_f32_16x16x32_bf16 v[96:99], v[168:171], v[194:197], v[96:99]
	v_mfma_f32_16x16x32_bf16 v[88:91], v[178:181], v[194:197], v[88:91]
	v_mfma_f32_16x16x32_bf16 v[80:83], v[168:171], v[202:205], v[80:83]
	v_mfma_f32_16x16x32_bf16 v[72:75], v[178:181], v[202:205], v[72:75]
	v_mfma_f32_16x16x32_bf16 v[68:71], v[168:171], v[210:213], v[68:71]
	v_mfma_f32_16x16x32_bf16 v[64:67], v[178:181], v[210:213], v[64:67]
	s_setprio 0
	s_barrier
; #define PG8_STAGE(bufoff, gbase, voff) do { _Pragma("unroll") for (int _i = 0; _i < 2; ++_i) \
;         __builtin_amdgcn_global_load_lds((const unsigned*)((const char*)(gbase) + (voff)[_i]), (PG8_LAS unsigned*)(lds + (bufoff) + ldsw + _i * 8192), 16, 0, 0); } while (0)
; #define PG8_LDA(dst, b, h) do { _Pragma("unroll") for (int m = 0; m < 4; ++m) _Pragma("unroll") for (int k = 0; k < 2; ++k) dst[m][k] = *(const PG8_LAS bf16x8*)(lds + PG8_SA(b, h) + aoff + m * 2048 + k * 1024); } while (0)
; #define PG8_MMA(ai, bj, At, Bt) do { __builtin_amdgcn_s_setprio(1); _Pragma("unroll") for (int m = 0; m < 4; ++m) _Pragma("unroll") for (int n = 0; n < 2; ++n) _Pragma("unroll") for (int k = 0; k < 2; ++k) \
;         acc[ai][bj][m][n] = __builtin_amdgcn_mfma_f32_16x16x32_bf16(Bt[n][k], At[m][k], acc[ai][bj][m][n], 0, 0, 0); __builtin_amdgcn_s_setprio(0); } while (0)
; #define PG8_WAIT_V(n) asm volatile("s_waitcnt vmcnt(" #n ")" ::: "memory")
; #define PG8_WAIT_L(n) asm volatile("s_waitcnt lgkmcnt(" #n ")" ::: "memory")
; #define PG8_BAR __builtin_amdgcn_s_barrier()
; #define PG8_SCHED __builtin_amdgcn_sched_barrier(0)
; template <class Epi, class Sched, bool ALIGN_EPI = false, bool SP2 = false>
; __device__ __forceinline__ void gemm_phase(PG8_LAS unsigned char* lds, const Gemm g, const Sched& S, const Epi& E) {
;     ...
;             PG8_LDA(At, 1, 1); PG8_STAGE(PG8_SB(1, 0), b3, voffB); PG8_STAGE(PG8_SB(1, 1), b3 + hstep, voffB); PG8_STAGE(PG8_SA(1, 0), a3, voffA);
;             PG8_WAIT_V(8); PG8_WAIT_L(0); PG8_BAR; PG8_MMA(1, 0, At, B0); PG8_MMA(1, 1, At, B1); PG8_BAR; PG8_SCHED;
	s_add_i32 s34, s34, s20
	v_lshl_add_u64 v[150:151], v[150:151], 0, s[22:23]
	s_mov_b32 m0, s34
	ds_read_b128 v[182:185], v155 offset:49152
	ds_read_b128 v[186:189], v155 offset:50176
	ds_read_b128 v[190:193], v155 offset:51200
	ds_read_b128 v[194:197], v155 offset:52224
	ds_read_b128 v[198:201], v155 offset:53248
	ds_read_b128 v[202:205], v155 offset:54272
	ds_read_b128 v[206:209], v155 offset:55296
	ds_read_b128 v[210:213], v155 offset:56320
	global_load_lds_dwordx4 v[150:151], off
	s_add_i32 m0, s34, 0x2000
	s_add_u32 s78, s82, 0x40080
	v_lshl_add_u64 v[150:151], v[214:215], 0, s[22:23]
	s_addc_u32 s79, s83, 0
	s_add_i32 s34, s35, s20
	global_load_lds_dwordx4 v[150:151], off
	v_lshl_add_u64 v[150:151], s[78:79], 0, v[162:163]
	s_mov_b32 m0, s34
	s_nop 0
	global_load_lds_dwordx4 v[150:151], off
	v_lshl_add_u64 v[150:151], s[78:79], 0, v[144:145]
	s_add_i32 m0, s34, 0x2000
	s_nop 0
	global_load_lds_dwordx4 v[150:151], off
	v_lshl_add_u64 v[150:151], v[216:217], 0, s[22:23]
	s_mov_b32 m0, s94
	s_nop 0
	global_load_lds_dwordx4 v[150:151], off
	v_lshl_add_u64 v[150:151], v[224:225], 0, s[22:23]
	s_mov_b32 m0, s95
	s_nop 0
	global_load_lds_dwordx4 v[150:151], off
	s_waitcnt vmcnt(8)
	s_waitcnt lgkmcnt(0)
	s_barrier
	s_setprio 1
	s_waitcnt lgkmcnt(0)
	v_mfma_f32_16x16x32_bf16 v[60:63], v[128:131], v[182:185], v[60:63]
	v_mfma_f32_16x16x32_bf16 v[56:59], v[136:139], v[182:185], v[56:59]
	v_mfma_f32_16x16x32_bf16 v[52:55], v[128:131], v[190:193], v[52:55]
	v_mfma_f32_16x16x32_bf16 v[44:47], v[136:139], v[190:193], v[44:47]
	v_mfma_f32_16x16x32_bf16 v[36:39], v[128:131], v[198:201], v[36:39]
	v_mfma_f32_16x16x32_bf16 v[28:31], v[136:139], v[198:201], v[28:31]
	v_mfma_f32_16x16x32_bf16 v[20:23], v[128:131], v[206:209], v[20:23]
	v_mfma_f32_16x16x32_bf16 v[12:15], v[136:139], v[206:209], v[12:15]
	v_mfma_f32_16x16x32_bf16 v[60:63], v[132:135], v[186:189], v[60:63]
	v_mfma_f32_16x16x32_bf16 v[56:59], v[140:143], v[186:189], v[56:59]
	v_mfma_f32_16x16x32_bf16 v[52:55], v[132:135], v[194:197], v[52:55]
	v_mfma_f32_16x16x32_bf16 v[44:47], v[140:143], v[194:197], v[44:47]
	v_mfma_f32_16x16x32_bf16 v[36:39], v[132:135], v[202:205], v[36:39]
	v_mfma_f32_16x16x32_bf16 v[28:31], v[140:143], v[202:205], v[28:31]
	v_mfma_f32_16x16x32_bf16 v[20:23], v[132:135], v[210:213], v[20:23]
	v_mfma_f32_16x16x32_bf16 v[12:15], v[140:143], v[210:213], v[12:15]
	s_setprio 0
	s_setprio 1
	v_mfma_f32_16x16x32_bf16 v[48:51], v[156:159], v[182:185], v[48:51]
	v_mfma_f32_16x16x32_bf16 v[40:43], v[172:175], v[182:185], v[40:43]
	v_mfma_f32_16x16x32_bf16 v[32:35], v[156:159], v[190:193], v[32:35]
	v_mfma_f32_16x16x32_bf16 v[24:27], v[172:175], v[190:193], v[24:27]
	v_mfma_f32_16x16x32_bf16 v[16:19], v[156:159], v[198:201], v[16:19]
	v_mfma_f32_16x16x32_bf16 v[8:11], v[172:175], v[198:201], v[8:11]
	v_mfma_f32_16x16x32_bf16 v[4:7], v[156:159], v[206:209], v[4:7]
	v_mfma_f32_16x16x32_bf16 v[0:3], v[172:175], v[206:209], v[0:3]
	v_mfma_f32_16x16x32_bf16 v[48:51], v[168:171], v[186:189], v[48:51]
	v_mfma_f32_16x16x32_bf16 v[40:43], v[178:181], v[186:189], v[40:43]
	v_mfma_f32_16x16x32_bf16 v[32:35], v[168:171], v[194:197], v[32:35]
	v_mfma_f32_16x16x32_bf16 v[24:27], v[178:181], v[194:197], v[24:27]
	v_mfma_f32_16x16x32_bf16 v[16:19], v[168:171], v[202:205], v[16:19]
	v_mfma_f32_16x16x32_bf16 v[8:11], v[178:181], v[202:205], v[8:11]
	v_mfma_f32_16x16x32_bf16 v[4:7], v[168:171], v[210:213], v[4:7]
	v_mfma_f32_16x16x32_bf16 v[0:3], v[178:181], v[210:213], v[0:3]
	s_setprio 0
	s_barrier
	s_add_i32 s19, s19, 2
	s_add_u32 vcc_lo, vcc_lo, 0x100
	s_addc_u32 vcc_hi, vcc_hi, 0
	s_cmp_gt_u32 s19, 13
	s_mov_b64 s[78:79], s[80:81]
	s_cbranch_scc0 .LBB0_1068
	s_and_b64 vcc, exec, s[66:67]
	s_cbranch_vccz .LBB0_1071
	s_barrier

; #define PG8_STAGE(bufoff, gbase, voff) do { _Pragma("unroll") for (int _i = 0; _i < 2; ++_i) \
;         __builtin_amdgcn_global_load_lds((const unsigned*)((const char*)(gbase) + (voff)[_i]), (PG8_LAS unsigned*)(lds + (bufoff) + ldsw + _i * 8192), 16, 0, 0); } while (0)
; #define PG8_LDA(dst, b, h) do { _Pragma("unroll") for (int m = 0; m < 4; ++m) _Pragma("unroll") for (int k = 0; k < 2; ++k) dst[m][k] = *(const PG8_LAS bf16x8*)(lds + PG8_SA(b, h) + aoff + m * 2048 + k * 1024); } while (0)
; #define PG8_LDB(dst, b, h) do { _Pragma("unroll") for (int n = 0; n < 2; ++n) _Pragma("unroll") for (int k = 0; k < 2; ++k) dst[n][k] = *(const PG8_LAS bf16x8*)(lds + PG8_SB(b, h) + boff + n * 2048 + k * 1024); } while (0)
; #define PG8_MMA(ai, bj, At, Bt) do { __builtin_amdgcn_s_setprio(1); _Pragma("unroll") for (int m = 0; m < 4; ++m) _Pragma("unroll") for (int n = 0; n < 2; ++n) _Pragma("unroll") for (int k = 0; k < 2; ++k) \
;         acc[ai][bj][m][n] = __builtin_amdgcn_mfma_f32_16x16x32_bf16(Bt[n][k], At[m][k], acc[ai][bj][m][n], 0, 0, 0); __builtin_amdgcn_s_setprio(0); } while (0)
; #define PG8_WAIT_V(n) asm volatile("s_waitcnt vmcnt(" #n ")" ::: "memory")
; #define PG8_WAIT_L(n) asm volatile("s_waitcnt lgkmcnt(" #n ")" ::: "memory")
; #define PG8_BAR __builtin_amdgcn_s_barrier()
; #define PG8_SCHED __builtin_amdgcn_sched_barrier(0)
; template <class Epi, class Sched, bool ALIGN_EPI = false, bool SP2 = false>
; __device__ __forceinline__ void gemm_phase(PG8_LAS unsigned char* lds, const Gemm g, const Sched& S, const Epi& E) {
;     ...
;             const bool last = (t == nt - 2);
;             const char* a1 = cA + (size_t)(t + 1) * kstep;
;             const char* a2 = last ? nA : cA + (size_t)(t + 2) * kstep; const char* b2 = last ? nB : cB + (size_t)(t + 2) * kstep;
;             const char* a3 = a2 + kstep; const char* b3 = b2 + kstep;
;             if (last && has_next) S.a_ready(nxt);
;             if constexpr (SP2) {
;             PG8_LDB(B0, 0, 0); PG8_LDB(B1, 0, 1); PG8_SCHED; PG8_LDA(At, 0, 0); PG8_STAGE(PG8_SA(1, 1), a1 + hstep, voffA);
;             PG8_WAIT_V(8); PG8_WAIT_L(0); PG8_BAR; PG8_MMA(0, 0, At, B0); PG8_MMA(0, 1, At, B1); PG8_BAR; PG8_SCHED;
;             PG8_LDA(At, 0, 1); PG8_STAGE(PG8_SB(0, 0), b2, voffB); PG8_STAGE(PG8_SB(0, 1), b2 + hstep, voffB); PG8_STAGE(PG8_SA(0, 0), a2, voffA);
.LBB0_1246:
	s_add_u32 s19, s74, 0xfffc0080
	s_addc_u32 s34, s75, -1
	s_add_i32 s35, 0, 0x10000
	s_cmp_eq_u32 s92, 12
	s_cselect_b32 s79, s16, s34
	s_cselect_b32 s78, s17, s19
	v_add_u32_e32 v142, s35, v145
	s_cselect_b32 s77, s18, s91
	s_cselect_b32 s76, s65, s67
	s_add_i32 s19, 0, 0x14000
	ds_read_b128 v[138:141], v142
	ds_read_b128 v[148:151], v142 offset:1024
	ds_read_b128 v[152:155], v142 offset:2048
	ds_read_b128 v[156:159], v142 offset:3072
	v_add_u32_e32 v142, s19, v145
	ds_read_b128 v[168:171], v142
	ds_read_b128 v[172:175], v142 offset:1024
	ds_read_b128 v[178:181], v142 offset:2048
	ds_read_b128 v[182:185], v142 offset:3072
	v_lshl_add_u64 v[142:143], s[74:75], 0, v[134:135]
	s_add_i32 m0, s73, 0xc000
	ds_read_b128 v[186:189], v147
	ds_read_b128 v[190:193], v147 offset:1024
	ds_read_b128 v[194:197], v147 offset:2048
	ds_read_b128 v[198:201], v147 offset:3072
	ds_read_b128 v[202:205], v147 offset:4096
	ds_read_b128 v[206:209], v147 offset:5120
	ds_read_b128 v[210:213], v147 offset:6144
	ds_read_b128 v[214:217], v147 offset:7168
	global_load_lds_dwordx4 v[142:143], off
	v_lshl_add_u64 v[142:143], s[74:75], 0, v[136:137]
	s_add_i32 m0, s73, 0xe000
	s_nop 0
	global_load_lds_dwordx4 v[142:143], off
	s_waitcnt vmcnt(8)
	s_waitcnt lgkmcnt(0)
	s_barrier
	s_setprio 1
	s_waitcnt lgkmcnt(0)
	v_mfma_f32_16x16x32_bf16 v[124:127], v[138:141], v[186:189], v[124:127]
	v_mfma_f32_16x16x32_bf16 v[120:123], v[152:155], v[186:189], v[120:123]
	v_mfma_f32_16x16x32_bf16 v[108:111], v[138:141], v[194:197], v[108:111]
	v_mfma_f32_16x16x32_bf16 v[104:107], v[152:155], v[194:197], v[104:107]
	v_mfma_f32_16x16x32_bf16 v[92:95], v[138:141], v[202:205], v[92:95]
	v_mfma_f32_16x16x32_bf16 v[88:91], v[152:155], v[202:205], v[88:91]
	v_mfma_f32_16x16x32_bf16 v[76:79], v[138:141], v[210:213], v[76:79]
	v_mfma_f32_16x16x32_bf16 v[72:75], v[152:155], v[210:213], v[72:75]
	v_mfma_f32_16x16x32_bf16 v[124:127], v[148:151], v[190:193], v[124:127]
	v_mfma_f32_16x16x32_bf16 v[120:123], v[156:159], v[190:193], v[120:123]
	v_mfma_f32_16x16x32_bf16 v[108:111], v[148:151], v[198:201], v[108:111]
	v_mfma_f32_16x16x32_bf16 v[104:107], v[156:159], v[198:201], v[104:107]
	v_mfma_f32_16x16x32_bf16 v[92:95], v[148:151], v[206:209], v[92:95]
	v_mfma_f32_16x16x32_bf16 v[88:91], v[156:159], v[206:209], v[88:91]
	v_mfma_f32_16x16x32_bf16 v[76:79], v[148:151], v[214:217], v[76:79]
	v_mfma_f32_16x16x32_bf16 v[72:75], v[156:159], v[214:217], v[72:75]
	s_setprio 0
	s_setprio 1
	v_mfma_f32_16x16x32_bf16 v[116:119], v[168:171], v[186:189], v[116:119]
	v_mfma_f32_16x16x32_bf16 v[112:115], v[178:181], v[186:189], v[112:115]
	v_mfma_f32_16x16x32_bf16 v[100:103], v[168:171], v[194:197], v[100:103]
	v_mfma_f32_16x16x32_bf16 v[96:99], v[178:181], v[194:197], v[96:99]
	v_mfma_f32_16x16x32_bf16 v[84:87], v[168:171], v[202:205], v[84:87]
	v_mfma_f32_16x16x32_bf16 v[80:83], v[178:181], v[202:205], v[80:83]
	v_mfma_f32_16x16x32_bf16 v[68:71], v[168:171], v[210:213], v[68:71]
	v_mfma_f32_16x16x32_bf16 v[64:67], v[178:181], v[210:213], v[64:67]
	v_mfma_f32_16x16x32_bf16 v[116:119], v[172:175], v[190:193], v[116:119]
	v_mfma_f32_16x16x32_bf16 v[112:115], v[182:185], v[190:193], v[112:115]
	v_mfma_f32_16x16x32_bf16 v[100:103], v[172:175], v[198:201], v[100:103]
	v_mfma_f32_16x16x32_bf16 v[96:99], v[182:185], v[198:201], v[96:99]
	v_mfma_f32_16x16x32_bf16 v[84:87], v[172:175], v[206:209], v[84:87]
	v_mfma_f32_16x16x32_bf16 v[80:83], v[182:185], v[206:209], v[80:83]
	v_mfma_f32_16x16x32_bf16 v[68:71], v[172:175], v[214:217], v[68:71]
	v_mfma_f32_16x16x32_bf16 v[64:67], v[182:185], v[214:217], v[64:67]
	s_setprio 0
	s_barrier
	s_add_i32 s34, s35, s82
	v_lshl_add_u64 v[142:143], s[76:77], 0, v[162:163]
	s_mov_b32 m0, s34
	ds_read_b128 v[186:189], v147 offset:16384
	ds_read_b128 v[190:193], v147 offset:17408
	ds_read_b128 v[194:197], v147 offset:18432
	ds_read_b128 v[198:201], v147 offset:19456
	ds_read_b128 v[202:205], v147 offset:20480
	ds_read_b128 v[206:209], v147 offset:21504
	ds_read_b128 v[210:213], v147 offset:22528
	ds_read_b128 v[214:217], v147 offset:23552
	global_load_lds_dwordx4 v[142:143], off
	s_add_i32 m0, s34, 0x2000
	s_add_u32 s94, s76, 0x40000
	v_lshl_add_u64 v[224:225], s[76:77], 0, v[132:133]
	s_addc_u32 s95, s77, 0
	s_add_i32 s19, s19, s82
	global_load_lds_dwordx4 v[224:225], off
	v_lshl_add_u64 v[226:227], s[94:95], 0, v[162:163]
	s_mov_b32 m0, s19
	v_lshl_add_u64 v[230:231], s[78:79], 0, v[130:131]
	global_load_lds_dwordx4 v[226:227], off
	v_lshl_add_u64 v[226:227], s[94:95], 0, v[132:133]
	s_add_i32 m0, s19, 0x2000
	s_nop 0
	global_load_lds_dwordx4 v[226:227], off
	v_lshl_add_u64 v[226:227], s[78:79], 0, v[128:129]
	s_waitcnt vmcnt(6)
	s_waitcnt lgkmcnt(0)
	s_barrier
; #define PG8_STAGE(bufoff, gbase, voff) do { _Pragma("unroll") for (int _i = 0; _i < 2; ++_i) \
;         __builtin_amdgcn_global_load_lds((const unsigned*)((const char*)(gbase) + (voff)[_i]), (PG8_LAS unsigned*)(lds + (bufoff) + ldsw + _i * 8192), 16, 0, 0); } while (0)
; #define PG8_LDA(dst, b, h) do { _Pragma("unroll") for (int m = 0; m < 4; ++m) _Pragma("unroll") for (int k = 0; k < 2; ++k) dst[m][k] = *(const PG8_LAS bf16x8*)(lds + PG8_SA(b, h) + aoff + m * 2048 + k * 1024); } while (0)
; #define PG8_LDB(dst, b, h) do { _Pragma("unroll") for (int n = 0; n < 2; ++n) _Pragma("unroll") for (int k = 0; k < 2; ++k) dst[n][k] = *(const PG8_LAS bf16x8*)(lds + PG8_SB(b, h) + boff + n * 2048 + k * 1024); } while (0)
; #define PG8_MMA(ai, bj, At, Bt) do { __builtin_amdgcn_s_setprio(1); _Pragma("unroll") for (int m = 0; m < 4; ++m) _Pragma("unroll") for (int n = 0; n < 2; ++n) _Pragma("unroll") for (int k = 0; k < 2; ++k) \
;         acc[ai][bj][m][n] = __builtin_amdgcn_mfma_f32_16x16x32_bf16(Bt[n][k], At[m][k], acc[ai][bj][m][n], 0, 0, 0); __builtin_amdgcn_s_setprio(0); } while (0)
; #define PG8_WAIT_V(n) asm volatile("s_waitcnt vmcnt(" #n ")" ::: "memory")
; #define PG8_WAIT_L(n) asm volatile("s_waitcnt lgkmcnt(" #n ")" ::: "memory")
; #define PG8_BAR __builtin_amdgcn_s_barrier()
; #define PG8_SCHED __builtin_amdgcn_sched_barrier(0)
; template <class Epi, class Sched, bool ALIGN_EPI = false, bool SP2 = false>
; __device__ __forceinline__ void gemm_phase(PG8_LAS unsigned char* lds, const Gemm g, const Sched& S, const Epi& E) {
;     ...
;             PG8_WAIT_V(8); PG8_WAIT_L(0); PG8_BAR; PG8_MMA(1, 0, At, B0); PG8_MMA(1, 1, At, B1); PG8_BAR; PG8_SCHED;
;             PG8_LDB(B0, 1, 0); PG8_LDB(B1, 1, 1); PG8_SCHED; PG8_LDA(At, 1, 0); PG8_STAGE(PG8_SA(0, 1), a2 + hstep, voffA);
;             PG8_WAIT_V(8); PG8_WAIT_L(0); PG8_BAR; PG8_MMA(0, 0, At, B0); PG8_MMA(0, 1, At, B1); PG8_BAR; PG8_SCHED;
;             PG8_LDA(At, 1, 1); PG8_STAGE(PG8_SB(1, 0), b3, voffB); PG8_STAGE(PG8_SB(1, 1), b3 + hstep, voffB); PG8_STAGE(PG8_SA(1, 0), a3, voffA);
	s_setprio 1
	s_waitcnt lgkmcnt(0)
	v_mfma_f32_16x16x32_bf16 v[60:63], v[138:141], v[186:189], v[60:63]
	v_mfma_f32_16x16x32_bf16 v[56:59], v[152:155], v[186:189], v[56:59]
	v_mfma_f32_16x16x32_bf16 v[44:47], v[138:141], v[194:197], v[44:47]
	v_mfma_f32_16x16x32_bf16 v[40:43], v[152:155], v[194:197], v[40:43]
	v_mfma_f32_16x16x32_bf16 v[28:31], v[138:141], v[202:205], v[28:31]
	v_mfma_f32_16x16x32_bf16 v[24:27], v[152:155], v[202:205], v[24:27]
	v_mfma_f32_16x16x32_bf16 v[12:15], v[138:141], v[210:213], v[12:15]
	v_mfma_f32_16x16x32_bf16 v[8:11], v[152:155], v[210:213], v[8:11]
	v_mfma_f32_16x16x32_bf16 v[60:63], v[148:151], v[190:193], v[60:63]
	v_mfma_f32_16x16x32_bf16 v[56:59], v[156:159], v[190:193], v[56:59]
	v_mfma_f32_16x16x32_bf16 v[44:47], v[148:151], v[198:201], v[44:47]
	v_mfma_f32_16x16x32_bf16 v[40:43], v[156:159], v[198:201], v[40:43]
	v_mfma_f32_16x16x32_bf16 v[28:31], v[148:151], v[206:209], v[28:31]
	v_mfma_f32_16x16x32_bf16 v[24:27], v[156:159], v[206:209], v[24:27]
	v_mfma_f32_16x16x32_bf16 v[12:15], v[148:151], v[214:217], v[12:15]
	v_mfma_f32_16x16x32_bf16 v[8:11], v[156:159], v[214:217], v[8:11]
	s_setprio 0
	s_setprio 1
	v_mfma_f32_16x16x32_bf16 v[52:55], v[168:171], v[186:189], v[52:55]
	v_mfma_f32_16x16x32_bf16 v[48:51], v[178:181], v[186:189], v[48:51]
	v_mfma_f32_16x16x32_bf16 v[36:39], v[168:171], v[194:197], v[36:39]
	v_mfma_f32_16x16x32_bf16 v[32:35], v[178:181], v[194:197], v[32:35]
	v_mfma_f32_16x16x32_bf16 v[20:23], v[168:171], v[202:205], v[20:23]
	v_mfma_f32_16x16x32_bf16 v[16:19], v[178:181], v[202:205], v[16:19]
	v_mfma_f32_16x16x32_bf16 v[4:7], v[168:171], v[210:213], v[4:7]
	v_mfma_f32_16x16x32_bf16 v[0:3], v[178:181], v[210:213], v[0:3]
	v_mfma_f32_16x16x32_bf16 v[52:55], v[172:175], v[190:193], v[52:55]
	v_mfma_f32_16x16x32_bf16 v[48:51], v[182:185], v[190:193], v[48:51]
	v_mfma_f32_16x16x32_bf16 v[36:39], v[172:175], v[198:201], v[36:39]
	v_mfma_f32_16x16x32_bf16 v[32:35], v[182:185], v[198:201], v[32:35]
	v_mfma_f32_16x16x32_bf16 v[20:23], v[172:175], v[206:209], v[20:23]
	v_mfma_f32_16x16x32_bf16 v[16:19], v[182:185], v[206:209], v[16:19]
	v_mfma_f32_16x16x32_bf16 v[4:7], v[172:175], v[214:217], v[4:7]
	v_mfma_f32_16x16x32_bf16 v[0:3], v[182:185], v[214:217], v[0:3]
	s_setprio 0
	s_barrier
	s_add_i32 s19, 0, 0x18000
	s_add_i32 s34, 0, 0x1c000
	v_add_u32_e32 v156, s19, v145
	v_add_u32_e32 v176, s34, v145
	ds_read_b128 v[138:141], v156
	ds_read_b128 v[148:151], v156 offset:1024
	ds_read_b128 v[152:155], v156 offset:2048
	ds_read_b128 v[156:159], v156 offset:3072
	ds_read_b128 v[168:171], v176
	ds_read_b128 v[172:175], v176 offset:1024
	ds_read_b128 v[178:181], v176 offset:2048
	ds_read_b128 v[182:185], v176 offset:3072
	s_add_u32 s78, s78, 0x40000
	s_addc_u32 s79, s79, 0
	s_mov_b32 m0, s73
	s_nop 0
	global_load_lds_dwordx4 v[226:227], off
	s_mov_b32 m0, s83
	s_nop 0
	global_load_lds_dwordx4 v[230:231], off
	s_mov_b32 m0, s84
	v_lshl_add_u64 v[232:233], s[78:79], 0, v[128:129]
	ds_read_b128 v[186:189], v147 offset:32768
	ds_read_b128 v[190:193], v147 offset:33792
	ds_read_b128 v[194:197], v147 offset:34816
	ds_read_b128 v[198:201], v147 offset:35840
	ds_read_b128 v[202:205], v147 offset:36864
	ds_read_b128 v[206:209], v147 offset:37888
	ds_read_b128 v[210:213], v147 offset:38912
	ds_read_b128 v[214:217], v147 offset:39936
	global_load_lds_dwordx4 v[232:233], off
	v_lshl_add_u64 v[232:233], s[78:79], 0, v[130:131]
	s_mov_b32 m0, s85
	s_nop 0
	global_load_lds_dwordx4 v[232:233], off
	s_waitcnt vmcnt(8)
	s_waitcnt lgkmcnt(0)
	s_barrier
	s_setprio 1
	s_waitcnt lgkmcnt(0)
	v_mfma_f32_16x16x32_bf16 v[124:127], v[138:141], v[186:189], v[124:127]
	v_mfma_f32_16x16x32_bf16 v[120:123], v[152:155], v[186:189], v[120:123]
	v_mfma_f32_16x16x32_bf16 v[108:111], v[138:141], v[194:197], v[108:111]
	v_mfma_f32_16x16x32_bf16 v[104:107], v[152:155], v[194:197], v[104:107]
	v_mfma_f32_16x16x32_bf16 v[92:95], v[138:141], v[202:205], v[92:95]
	v_mfma_f32_16x16x32_bf16 v[88:91], v[152:155], v[202:205], v[88:91]
	v_mfma_f32_16x16x32_bf16 v[76:79], v[138:141], v[210:213], v[76:79]
	v_mfma_f32_16x16x32_bf16 v[72:75], v[152:155], v[210:213], v[72:75]
	v_mfma_f32_16x16x32_bf16 v[124:127], v[148:151], v[190:193], v[124:127]
	v_mfma_f32_16x16x32_bf16 v[120:123], v[156:159], v[190:193], v[120:123]
	v_mfma_f32_16x16x32_bf16 v[108:111], v[148:151], v[198:201], v[108:111]
	v_mfma_f32_16x16x32_bf16 v[104:107], v[156:159], v[198:201], v[104:107]
	v_mfma_f32_16x16x32_bf16 v[92:95], v[148:151], v[206:209], v[92:95]
	v_mfma_f32_16x16x32_bf16 v[88:91], v[156:159], v[206:209], v[88:91]
	v_mfma_f32_16x16x32_bf16 v[76:79], v[148:151], v[214:217], v[76:79]
	v_mfma_f32_16x16x32_bf16 v[72:75], v[156:159], v[214:217], v[72:75]
	s_setprio 0
	s_setprio 1
	v_mfma_f32_16x16x32_bf16 v[116:119], v[168:171], v[186:189], v[116:119]
	v_mfma_f32_16x16x32_bf16 v[112:115], v[178:181], v[186:189], v[112:115]
	v_mfma_f32_16x16x32_bf16 v[100:103], v[168:171], v[194:197], v[100:103]
	v_mfma_f32_16x16x32_bf16 v[96:99], v[178:181], v[194:197], v[96:99]
	v_mfma_f32_16x16x32_bf16 v[84:87], v[168:171], v[202:205], v[84:87]
	v_mfma_f32_16x16x32_bf16 v[80:83], v[178:181], v[202:205], v[80:83]
	v_mfma_f32_16x16x32_bf16 v[68:71], v[168:171], v[210:213], v[68:71]
	v_mfma_f32_16x16x32_bf16 v[64:67], v[178:181], v[210:213], v[64:67]
	v_mfma_f32_16x16x32_bf16 v[116:119], v[172:175], v[190:193], v[116:119]
	v_mfma_f32_16x16x32_bf16 v[112:115], v[182:185], v[190:193], v[112:115]
	v_mfma_f32_16x16x32_bf16 v[100:103], v[172:175], v[198:201], v[100:103]
	v_mfma_f32_16x16x32_bf16 v[96:99], v[182:185], v[198:201], v[96:99]
	v_mfma_f32_16x16x32_bf16 v[84:87], v[172:175], v[206:209], v[84:87]
	v_mfma_f32_16x16x32_bf16 v[80:83], v[182:185], v[206:209], v[80:83]
	v_mfma_f32_16x16x32_bf16 v[68:71], v[172:175], v[214:217], v[68:71]
	v_mfma_f32_16x16x32_bf16 v[64:67], v[182:185], v[214:217], v[64:67]
	s_setprio 0
	s_barrier
; #define PG8_STAGE(bufoff, gbase, voff) do { _Pragma("unroll") for (int _i = 0; _i < 2; ++_i) \
;         __builtin_amdgcn_global_load_lds((const unsigned*)((const char*)(gbase) + (voff)[_i]), (PG8_LAS unsigned*)(lds + (bufoff) + ldsw + _i * 8192), 16, 0, 0); } while (0)
; #define PG8_LDA(dst, b, h) do { _Pragma("unroll") for (int m = 0; m < 4; ++m) _Pragma("unroll") for (int k = 0; k < 2; ++k) dst[m][k] = *(const PG8_LAS bf16x8*)(lds + PG8_SA(b, h) + aoff + m * 2048 + k * 1024); } while (0)
; #define PG8_MMA(ai, bj, At, Bt) do { __builtin_amdgcn_s_setprio(1); _Pragma("unroll") for (int m = 0; m < 4; ++m) _Pragma("unroll") for (int n = 0; n < 2; ++n) _Pragma("unroll") for (int k = 0; k < 2; ++k) \
;         acc[ai][bj][m][n] = __builtin_amdgcn_mfma_f32_16x16x32_bf16(Bt[n][k], At[m][k], acc[ai][bj][m][n], 0, 0, 0); __builtin_amdgcn_s_setprio(0); } while (0)
; #define PG8_WAIT_V(n) asm volatile("s_waitcnt vmcnt(" #n ")" ::: "memory")
; #define PG8_WAIT_L(n) asm volatile("s_waitcnt lgkmcnt(" #n ")" ::: "memory")
; #define PG8_BAR __builtin_amdgcn_s_barrier()
; #define PG8_SCHED __builtin_amdgcn_sched_barrier(0)
; template <class Epi, class Sched, bool ALIGN_EPI = false, bool SP2 = false>
; __device__ __forceinline__ void gemm_phase(PG8_LAS unsigned char* lds, const Gemm g, const Sched& S, const Epi& E) {
;     ...
;             PG8_LDA(At, 1, 1); PG8_STAGE(PG8_SB(1, 0), b3, voffB); PG8_STAGE(PG8_SB(1, 1), b3 + hstep, voffB); PG8_STAGE(PG8_SA(1, 0), a3, voffA);
;             PG8_WAIT_V(8); PG8_WAIT_L(0); PG8_BAR; PG8_MMA(1, 0, At, B0); PG8_MMA(1, 1, At, B1); PG8_BAR; PG8_SCHED;
	s_add_i32 s19, s19, s82
	v_lshl_add_u64 v[142:143], v[142:143], 0, s[22:23]
	s_mov_b32 m0, s19
	ds_read_b128 v[186:189], v147 offset:49152
	ds_read_b128 v[190:193], v147 offset:50176
	ds_read_b128 v[194:197], v147 offset:51200
	ds_read_b128 v[198:201], v147 offset:52224
	ds_read_b128 v[202:205], v147 offset:53248
	ds_read_b128 v[206:209], v147 offset:54272
	ds_read_b128 v[210:213], v147 offset:55296
	ds_read_b128 v[214:217], v147 offset:56320
	global_load_lds_dwordx4 v[142:143], off
	s_add_i32 m0, s19, 0x2000
	s_add_u32 s76, s76, 0x40080
	v_lshl_add_u64 v[142:143], v[224:225], 0, s[22:23]
	s_addc_u32 s77, s77, 0
	s_add_i32 s19, s34, s82
	global_load_lds_dwordx4 v[142:143], off
	v_lshl_add_u64 v[142:143], s[76:77], 0, v[162:163]
	s_mov_b32 m0, s19
	s_nop 0
	global_load_lds_dwordx4 v[142:143], off
	v_lshl_add_u64 v[142:143], s[76:77], 0, v[132:133]
	s_add_i32 m0, s19, 0x2000
	s_nop 0
	global_load_lds_dwordx4 v[142:143], off
	v_lshl_add_u64 v[142:143], v[226:227], 0, s[22:23]
	s_mov_b32 m0, s86
	s_nop 0
	global_load_lds_dwordx4 v[142:143], off
	v_lshl_add_u64 v[142:143], v[230:231], 0, s[22:23]
	s_mov_b32 m0, s87
	s_nop 0
	global_load_lds_dwordx4 v[142:143], off
	s_waitcnt vmcnt(8)
	s_waitcnt lgkmcnt(0)
	s_barrier
	s_setprio 1
	s_waitcnt lgkmcnt(0)
	v_mfma_f32_16x16x32_bf16 v[60:63], v[138:141], v[186:189], v[60:63]
	v_mfma_f32_16x16x32_bf16 v[56:59], v[152:155], v[186:189], v[56:59]
	v_mfma_f32_16x16x32_bf16 v[44:47], v[138:141], v[194:197], v[44:47]
	v_mfma_f32_16x16x32_bf16 v[40:43], v[152:155], v[194:197], v[40:43]
	v_mfma_f32_16x16x32_bf16 v[28:31], v[138:141], v[202:205], v[28:31]
	v_mfma_f32_16x16x32_bf16 v[24:27], v[152:155], v[202:205], v[24:27]
	v_mfma_f32_16x16x32_bf16 v[12:15], v[138:141], v[210:213], v[12:15]
	v_mfma_f32_16x16x32_bf16 v[8:11], v[152:155], v[210:213], v[8:11]
	v_mfma_f32_16x16x32_bf16 v[60:63], v[148:151], v[190:193], v[60:63]
	v_mfma_f32_16x16x32_bf16 v[56:59], v[156:159], v[190:193], v[56:59]
	v_mfma_f32_16x16x32_bf16 v[44:47], v[148:151], v[198:201], v[44:47]
	v_mfma_f32_16x16x32_bf16 v[40:43], v[156:159], v[198:201], v[40:43]
	v_mfma_f32_16x16x32_bf16 v[28:31], v[148:151], v[206:209], v[28:31]
	v_mfma_f32_16x16x32_bf16 v[24:27], v[156:159], v[206:209], v[24:27]
	v_mfma_f32_16x16x32_bf16 v[12:15], v[148:151], v[214:217], v[12:15]
	v_mfma_f32_16x16x32_bf16 v[8:11], v[156:159], v[214:217], v[8:11]
	s_setprio 0
	s_setprio 1
	v_mfma_f32_16x16x32_bf16 v[52:55], v[168:171], v[186:189], v[52:55]
	v_mfma_f32_16x16x32_bf16 v[48:51], v[178:181], v[186:189], v[48:51]
	v_mfma_f32_16x16x32_bf16 v[36:39], v[168:171], v[194:197], v[36:39]
	v_mfma_f32_16x16x32_bf16 v[32:35], v[178:181], v[194:197], v[32:35]
	v_mfma_f32_16x16x32_bf16 v[20:23], v[168:171], v[202:205], v[20:23]
	v_mfma_f32_16x16x32_bf16 v[16:19], v[178:181], v[202:205], v[16:19]
	v_mfma_f32_16x16x32_bf16 v[4:7], v[168:171], v[210:213], v[4:7]
	v_mfma_f32_16x16x32_bf16 v[0:3], v[178:181], v[210:213], v[0:3]
	v_mfma_f32_16x16x32_bf16 v[52:55], v[172:175], v[190:193], v[52:55]
	v_mfma_f32_16x16x32_bf16 v[48:51], v[182:185], v[190:193], v[48:51]
	v_mfma_f32_16x16x32_bf16 v[36:39], v[172:175], v[198:201], v[36:39]
	v_mfma_f32_16x16x32_bf16 v[32:35], v[182:185], v[198:201], v[32:35]
	v_mfma_f32_16x16x32_bf16 v[20:23], v[172:175], v[206:209], v[20:23]
	v_mfma_f32_16x16x32_bf16 v[16:19], v[182:185], v[206:209], v[16:19]
	v_mfma_f32_16x16x32_bf16 v[4:7], v[172:175], v[214:217], v[4:7]
	v_mfma_f32_16x16x32_bf16 v[0:3], v[182:185], v[214:217], v[0:3]
	s_setprio 0
	s_barrier
	s_add_i32 s92, s92, 2
	s_add_u32 s74, s74, 0x100
	s_addc_u32 s75, s75, 0
	s_add_u32 s67, s67, 0x100
	s_addc_u32 s91, s91, 0
	s_cmp_gt_u32 s92, 13
	s_cbranch_scc0 .LBB0_1246
	s_and_b64 vcc, exec, s[6:7]
	s_cbranch_vccz .LBB0_1249
	s_barrier

; #define PG8_STAGE(bufoff, gbase, voff) do { _Pragma("unroll") for (int _i = 0; _i < 2; ++_i) \
;         __builtin_amdgcn_global_load_lds((const unsigned*)((const char*)(gbase) + (voff)[_i]), (PG8_LAS unsigned*)(lds + (bufoff) + ldsw + _i * 8192), 16, 0, 0); } while (0)
; #define PG8_LDA(dst, b, h) do { _Pragma("unroll") for (int m = 0; m < 4; ++m) _Pragma("unroll") for (int k = 0; k < 2; ++k) dst[m][k] = *(const PG8_LAS bf16x8*)(lds + PG8_SA(b, h) + aoff + m * 2048 + k * 1024); } while (0)
; #define PG8_LDB(dst, b, h) do { _Pragma("unroll") for (int n = 0; n < 2; ++n) _Pragma("unroll") for (int k = 0; k < 2; ++k) dst[n][k] = *(const PG8_LAS bf16x8*)(lds + PG8_SB(b, h) + boff + n * 2048 + k * 1024); } while (0)
; #define PG8_MMA(ai, bj, At, Bt) do { __builtin_amdgcn_s_setprio(1); _Pragma("unroll") for (int m = 0; m < 4; ++m) _Pragma("unroll") for (int n = 0; n < 2; ++n) _Pragma("unroll") for (int k = 0; k < 2; ++k) \
;         acc[ai][bj][m][n] = __builtin_amdgcn_mfma_f32_16x16x32_bf16(Bt[n][k], At[m][k], acc[ai][bj][m][n], 0, 0, 0); __builtin_amdgcn_s_setprio(0); } while (0)
; #define PG8_WAIT_V(n) asm volatile("s_waitcnt vmcnt(" #n ")" ::: "memory")
; #define PG8_WAIT_L(n) asm volatile("s_waitcnt lgkmcnt(" #n ")" ::: "memory")
; #define PG8_BAR __builtin_amdgcn_s_barrier()
; #define PG8_SCHED __builtin_amdgcn_sched_barrier(0)
; template <class Epi, class Sched, bool ALIGN_EPI = false, bool SP2 = false>
; __device__ __forceinline__ void gemm_phase(PG8_LAS unsigned char* lds, const Gemm g, const Sched& S, const Epi& E) {
;     ...
;             const bool last = (t == nt - 2);
;             const char* a1 = cA + (size_t)(t + 1) * kstep;
;             const char* a2 = last ? nA : cA + (size_t)(t + 2) * kstep; const char* b2 = last ? nB : cB + (size_t)(t + 2) * kstep;
;             const char* a3 = a2 + kstep; const char* b3 = b2 + kstep;
;             if (last && has_next) S.a_ready(nxt);
;             if constexpr (SP2) {
;             PG8_LDB(B0, 0, 0); PG8_LDB(B1, 0, 1); PG8_SCHED; PG8_LDA(At, 0, 0); PG8_STAGE(PG8_SA(1, 1), a1 + hstep, voffA);
;             PG8_WAIT_V(8); PG8_WAIT_L(0); PG8_BAR; PG8_MMA(0, 0, At, B0); PG8_MMA(0, 1, At, B1); PG8_BAR; PG8_SCHED;
;             PG8_LDA(At, 0, 1); PG8_STAGE(PG8_SB(0, 0), b2, voffB); PG8_STAGE(PG8_SB(0, 1), b2 + hstep, voffB); PG8_STAGE(PG8_SA(0, 0), a2, voffA);
.LBB0_1332:
	s_add_u32 s76, s74, 0x100
	s_addc_u32 s77, s75, 0
	s_add_i32 s34, 0, 0x10000
	s_cmp_eq_u32 s19, 60
	s_cselect_b32 s81, s16, s77
	s_cselect_b32 s80, s17, s76
	s_cselect_b32 s79, s65, s94
	s_cselect_b32 s78, s67, s93
	s_add_i32 s35, 0, 0x14000
	v_add_u32_e32 v140, s34, v153
	v_add_u32_e32 v150, s35, v153
	ds_read_b128 v[128:131], v140
	ds_read_b128 v[132:135], v140 offset:1024
	ds_read_b128 v[136:139], v140 offset:2048
	ds_read_b128 v[140:143], v140 offset:3072
	ds_read_b128 v[156:159], v150
	ds_read_b128 v[168:171], v150 offset:1024
	ds_read_b128 v[172:175], v150 offset:2048
	ds_read_b128 v[178:181], v150 offset:3072
	v_lshl_add_u64 v[150:151], s[74:75], 0, v[146:147]
	s_add_i32 m0, s73, 0xc000
	ds_read_b128 v[182:185], v155
	ds_read_b128 v[186:189], v155 offset:1024
	ds_read_b128 v[190:193], v155 offset:2048
	ds_read_b128 v[194:197], v155 offset:3072
	ds_read_b128 v[198:201], v155 offset:4096
	ds_read_b128 v[202:205], v155 offset:5120
	ds_read_b128 v[206:209], v155 offset:6144
	ds_read_b128 v[210:213], v155 offset:7168
	global_load_lds_dwordx4 v[150:151], off
	v_lshl_add_u64 v[150:151], s[74:75], 0, v[148:149]
	s_add_i32 m0, s73, 0xe000
	s_nop 0
	global_load_lds_dwordx4 v[150:151], off
	s_waitcnt vmcnt(8)
	s_waitcnt lgkmcnt(0)
	s_barrier
	s_setprio 1
	s_waitcnt lgkmcnt(0)
	v_mfma_f32_16x16x32_bf16 v[124:127], v[128:131], v[182:185], v[124:127]
	v_mfma_f32_16x16x32_bf16 v[120:123], v[136:139], v[182:185], v[120:123]
	v_mfma_f32_16x16x32_bf16 v[116:119], v[128:131], v[190:193], v[116:119]
	v_mfma_f32_16x16x32_bf16 v[108:111], v[136:139], v[190:193], v[108:111]
	v_mfma_f32_16x16x32_bf16 v[100:103], v[128:131], v[198:201], v[100:103]
	v_mfma_f32_16x16x32_bf16 v[92:95], v[136:139], v[198:201], v[92:95]
	v_mfma_f32_16x16x32_bf16 v[84:87], v[128:131], v[206:209], v[84:87]
	v_mfma_f32_16x16x32_bf16 v[76:79], v[136:139], v[206:209], v[76:79]
	v_mfma_f32_16x16x32_bf16 v[124:127], v[132:135], v[186:189], v[124:127]
	v_mfma_f32_16x16x32_bf16 v[120:123], v[140:143], v[186:189], v[120:123]
	v_mfma_f32_16x16x32_bf16 v[116:119], v[132:135], v[194:197], v[116:119]
	v_mfma_f32_16x16x32_bf16 v[108:111], v[140:143], v[194:197], v[108:111]
	v_mfma_f32_16x16x32_bf16 v[100:103], v[132:135], v[202:205], v[100:103]
	v_mfma_f32_16x16x32_bf16 v[92:95], v[140:143], v[202:205], v[92:95]
	v_mfma_f32_16x16x32_bf16 v[84:87], v[132:135], v[210:213], v[84:87]
	v_mfma_f32_16x16x32_bf16 v[76:79], v[140:143], v[210:213], v[76:79]
	s_setprio 0
	s_setprio 1
	v_mfma_f32_16x16x32_bf16 v[112:115], v[156:159], v[182:185], v[112:115]
	v_mfma_f32_16x16x32_bf16 v[104:107], v[172:175], v[182:185], v[104:107]
	v_mfma_f32_16x16x32_bf16 v[96:99], v[156:159], v[190:193], v[96:99]
	v_mfma_f32_16x16x32_bf16 v[88:91], v[172:175], v[190:193], v[88:91]
	v_mfma_f32_16x16x32_bf16 v[80:83], v[156:159], v[198:201], v[80:83]
	v_mfma_f32_16x16x32_bf16 v[72:75], v[172:175], v[198:201], v[72:75]
	v_mfma_f32_16x16x32_bf16 v[68:71], v[156:159], v[206:209], v[68:71]
	v_mfma_f32_16x16x32_bf16 v[64:67], v[172:175], v[206:209], v[64:67]
	v_mfma_f32_16x16x32_bf16 v[112:115], v[168:171], v[186:189], v[112:115]
	v_mfma_f32_16x16x32_bf16 v[104:107], v[178:181], v[186:189], v[104:107]
	v_mfma_f32_16x16x32_bf16 v[96:99], v[168:171], v[194:197], v[96:99]
	v_mfma_f32_16x16x32_bf16 v[88:91], v[178:181], v[194:197], v[88:91]
	v_mfma_f32_16x16x32_bf16 v[80:83], v[168:171], v[202:205], v[80:83]
	v_mfma_f32_16x16x32_bf16 v[72:75], v[178:181], v[202:205], v[72:75]
	v_mfma_f32_16x16x32_bf16 v[68:71], v[168:171], v[210:213], v[68:71]
	v_mfma_f32_16x16x32_bf16 v[64:67], v[178:181], v[210:213], v[64:67]
	s_setprio 0
	s_barrier
	s_add_i32 s34, s34, s83
	v_lshl_add_u64 v[150:151], s[78:79], 0, v[162:163]
	s_mov_b32 m0, s34
	ds_read_b128 v[182:185], v155 offset:16384
	ds_read_b128 v[186:189], v155 offset:17408
	ds_read_b128 v[190:193], v155 offset:18432
	ds_read_b128 v[194:197], v155 offset:19456
	ds_read_b128 v[198:201], v155 offset:20480
	ds_read_b128 v[202:205], v155 offset:21504
	ds_read_b128 v[206:209], v155 offset:22528
	ds_read_b128 v[210:213], v155 offset:23552
	global_load_lds_dwordx4 v[150:151], off
	s_add_i32 m0, s34, 0x2000
	s_add_u32 s74, s78, 0x100000
	v_lshl_add_u64 v[214:215], s[78:79], 0, v[144:145]
	s_addc_u32 s75, s79, 0
	s_add_i32 s34, s35, s83
	global_load_lds_dwordx4 v[214:215], off
	v_lshl_add_u64 v[216:217], s[74:75], 0, v[162:163]
	s_mov_b32 m0, s34
	v_lshl_add_u64 v[224:225], s[80:81], 0, v[144:145]
	global_load_lds_dwordx4 v[216:217], off
	v_lshl_add_u64 v[216:217], s[74:75], 0, v[144:145]
	s_add_i32 m0, s34, 0x2000
	s_nop 0
	global_load_lds_dwordx4 v[216:217], off
	v_lshl_add_u64 v[216:217], s[80:81], 0, v[162:163]
	s_waitcnt vmcnt(6)
	s_waitcnt lgkmcnt(0)
	s_barrier
; #define PG8_STAGE(bufoff, gbase, voff) do { _Pragma("unroll") for (int _i = 0; _i < 2; ++_i) \
;         __builtin_amdgcn_global_load_lds((const unsigned*)((const char*)(gbase) + (voff)[_i]), (PG8_LAS unsigned*)(lds + (bufoff) + ldsw + _i * 8192), 16, 0, 0); } while (0)
; #define PG8_LDA(dst, b, h) do { _Pragma("unroll") for (int m = 0; m < 4; ++m) _Pragma("unroll") for (int k = 0; k < 2; ++k) dst[m][k] = *(const PG8_LAS bf16x8*)(lds + PG8_SA(b, h) + aoff + m * 2048 + k * 1024); } while (0)
; #define PG8_LDB(dst, b, h) do { _Pragma("unroll") for (int n = 0; n < 2; ++n) _Pragma("unroll") for (int k = 0; k < 2; ++k) dst[n][k] = *(const PG8_LAS bf16x8*)(lds + PG8_SB(b, h) + boff + n * 2048 + k * 1024); } while (0)
; #define PG8_MMA(ai, bj, At, Bt) do { __builtin_amdgcn_s_setprio(1); _Pragma("unroll") for (int m = 0; m < 4; ++m) _Pragma("unroll") for (int n = 0; n < 2; ++n) _Pragma("unroll") for (int k = 0; k < 2; ++k) \
;         acc[ai][bj][m][n] = __builtin_amdgcn_mfma_f32_16x16x32_bf16(Bt[n][k], At[m][k], acc[ai][bj][m][n], 0, 0, 0); __builtin_amdgcn_s_setprio(0); } while (0)
; #define PG8_WAIT_V(n) asm volatile("s_waitcnt vmcnt(" #n ")" ::: "memory")
; #define PG8_WAIT_L(n) asm volatile("s_waitcnt lgkmcnt(" #n ")" ::: "memory")
; #define PG8_BAR __builtin_amdgcn_s_barrier()
; #define PG8_SCHED __builtin_amdgcn_sched_barrier(0)
; template <class Epi, class Sched, bool ALIGN_EPI = false, bool SP2 = false>
; __device__ __forceinline__ void gemm_phase(PG8_LAS unsigned char* lds, const Gemm g, const Sched& S, const Epi& E) {
;     ...
;             PG8_WAIT_V(8); PG8_WAIT_L(0); PG8_BAR; PG8_MMA(1, 0, At, B0); PG8_MMA(1, 1, At, B1); PG8_BAR; PG8_SCHED;
;             PG8_LDB(B0, 1, 0); PG8_LDB(B1, 1, 1); PG8_SCHED; PG8_LDA(At, 1, 0); PG8_STAGE(PG8_SA(0, 1), a2 + hstep, voffA);
;             PG8_WAIT_V(8); PG8_WAIT_L(0); PG8_BAR; PG8_MMA(0, 0, At, B0); PG8_MMA(0, 1, At, B1); PG8_BAR; PG8_SCHED;
;             PG8_LDA(At, 1, 1); PG8_STAGE(PG8_SB(1, 0), b3, voffB); PG8_STAGE(PG8_SB(1, 1), b3 + hstep, voffB); PG8_STAGE(PG8_SA(1, 0), a3, voffA);
	s_setprio 1
	s_waitcnt lgkmcnt(0)
	v_mfma_f32_16x16x32_bf16 v[60:63], v[128:131], v[182:185], v[60:63]
	v_mfma_f32_16x16x32_bf16 v[56:59], v[136:139], v[182:185], v[56:59]
	v_mfma_f32_16x16x32_bf16 v[52:55], v[128:131], v[190:193], v[52:55]
	v_mfma_f32_16x16x32_bf16 v[44:47], v[136:139], v[190:193], v[44:47]
	v_mfma_f32_16x16x32_bf16 v[36:39], v[128:131], v[198:201], v[36:39]
	v_mfma_f32_16x16x32_bf16 v[28:31], v[136:139], v[198:201], v[28:31]
	v_mfma_f32_16x16x32_bf16 v[20:23], v[128:131], v[206:209], v[20:23]
	v_mfma_f32_16x16x32_bf16 v[12:15], v[136:139], v[206:209], v[12:15]
	v_mfma_f32_16x16x32_bf16 v[60:63], v[132:135], v[186:189], v[60:63]
	v_mfma_f32_16x16x32_bf16 v[56:59], v[140:143], v[186:189], v[56:59]
	v_mfma_f32_16x16x32_bf16 v[52:55], v[132:135], v[194:197], v[52:55]
	v_mfma_f32_16x16x32_bf16 v[44:47], v[140:143], v[194:197], v[44:47]
	v_mfma_f32_16x16x32_bf16 v[36:39], v[132:135], v[202:205], v[36:39]
	v_mfma_f32_16x16x32_bf16 v[28:31], v[140:143], v[202:205], v[28:31]
	v_mfma_f32_16x16x32_bf16 v[20:23], v[132:135], v[210:213], v[20:23]
	v_mfma_f32_16x16x32_bf16 v[12:15], v[140:143], v[210:213], v[12:15]
	s_setprio 0
	s_setprio 1
	v_mfma_f32_16x16x32_bf16 v[48:51], v[156:159], v[182:185], v[48:51]
	v_mfma_f32_16x16x32_bf16 v[40:43], v[172:175], v[182:185], v[40:43]
	v_mfma_f32_16x16x32_bf16 v[32:35], v[156:159], v[190:193], v[32:35]
	v_mfma_f32_16x16x32_bf16 v[24:27], v[172:175], v[190:193], v[24:27]
	v_mfma_f32_16x16x32_bf16 v[16:19], v[156:159], v[198:201], v[16:19]
	v_mfma_f32_16x16x32_bf16 v[8:11], v[172:175], v[198:201], v[8:11]
	v_mfma_f32_16x16x32_bf16 v[4:7], v[156:159], v[206:209], v[4:7]
	v_mfma_f32_16x16x32_bf16 v[0:3], v[172:175], v[206:209], v[0:3]
	v_mfma_f32_16x16x32_bf16 v[48:51], v[168:171], v[186:189], v[48:51]
	v_mfma_f32_16x16x32_bf16 v[40:43], v[178:181], v[186:189], v[40:43]
	v_mfma_f32_16x16x32_bf16 v[32:35], v[168:171], v[194:197], v[32:35]
	v_mfma_f32_16x16x32_bf16 v[24:27], v[178:181], v[194:197], v[24:27]
	v_mfma_f32_16x16x32_bf16 v[16:19], v[168:171], v[202:205], v[16:19]
	v_mfma_f32_16x16x32_bf16 v[8:11], v[178:181], v[202:205], v[8:11]
	v_mfma_f32_16x16x32_bf16 v[4:7], v[168:171], v[210:213], v[4:7]
	v_mfma_f32_16x16x32_bf16 v[0:3], v[178:181], v[210:213], v[0:3]
	s_setprio 0
	s_barrier
	s_add_i32 s34, 0, 0x18000
	s_add_i32 s35, 0, 0x1c000
	v_add_u32_e32 v140, s34, v153
	v_add_u32_e32 v176, s35, v153
	ds_read_b128 v[128:131], v140
	ds_read_b128 v[132:135], v140 offset:1024
	ds_read_b128 v[136:139], v140 offset:2048
	ds_read_b128 v[140:143], v140 offset:3072
	ds_read_b128 v[156:159], v176
	ds_read_b128 v[168:171], v176 offset:1024
	ds_read_b128 v[172:175], v176 offset:2048
	ds_read_b128 v[178:181], v176 offset:3072
	s_add_u32 s74, s80, 0x100000
	s_addc_u32 s75, s81, 0
	s_mov_b32 m0, s73
	s_nop 0
	global_load_lds_dwordx4 v[216:217], off
	s_mov_b32 m0, s84
	s_nop 0
	global_load_lds_dwordx4 v[224:225], off
	s_mov_b32 m0, s85
	v_lshl_add_u64 v[226:227], s[74:75], 0, v[162:163]
	ds_read_b128 v[182:185], v155 offset:32768
	ds_read_b128 v[186:189], v155 offset:33792
	ds_read_b128 v[190:193], v155 offset:34816
	ds_read_b128 v[194:197], v155 offset:35840
	ds_read_b128 v[198:201], v155 offset:36864
	ds_read_b128 v[202:205], v155 offset:37888
	ds_read_b128 v[206:209], v155 offset:38912
	ds_read_b128 v[210:213], v155 offset:39936
	global_load_lds_dwordx4 v[226:227], off
	v_lshl_add_u64 v[226:227], s[74:75], 0, v[144:145]
	s_mov_b32 m0, s86
	s_nop 0
	global_load_lds_dwordx4 v[226:227], off
	s_waitcnt vmcnt(8)
	s_waitcnt lgkmcnt(0)
	s_barrier
	s_setprio 1
	s_waitcnt lgkmcnt(0)
	v_mfma_f32_16x16x32_bf16 v[124:127], v[128:131], v[182:185], v[124:127]
	v_mfma_f32_16x16x32_bf16 v[120:123], v[136:139], v[182:185], v[120:123]
	v_mfma_f32_16x16x32_bf16 v[116:119], v[128:131], v[190:193], v[116:119]
	v_mfma_f32_16x16x32_bf16 v[108:111], v[136:139], v[190:193], v[108:111]
	v_mfma_f32_16x16x32_bf16 v[100:103], v[128:131], v[198:201], v[100:103]
	v_mfma_f32_16x16x32_bf16 v[92:95], v[136:139], v[198:201], v[92:95]
	v_mfma_f32_16x16x32_bf16 v[84:87], v[128:131], v[206:209], v[84:87]
	v_mfma_f32_16x16x32_bf16 v[76:79], v[136:139], v[206:209], v[76:79]
	v_mfma_f32_16x16x32_bf16 v[124:127], v[132:135], v[186:189], v[124:127]
	v_mfma_f32_16x16x32_bf16 v[120:123], v[140:143], v[186:189], v[120:123]
	v_mfma_f32_16x16x32_bf16 v[116:119], v[132:135], v[194:197], v[116:119]
	v_mfma_f32_16x16x32_bf16 v[108:111], v[140:143], v[194:197], v[108:111]
	v_mfma_f32_16x16x32_bf16 v[100:103], v[132:135], v[202:205], v[100:103]
	v_mfma_f32_16x16x32_bf16 v[92:95], v[140:143], v[202:205], v[92:95]
	v_mfma_f32_16x16x32_bf16 v[84:87], v[132:135], v[210:213], v[84:87]
	v_mfma_f32_16x16x32_bf16 v[76:79], v[140:143], v[210:213], v[76:79]
	s_setprio 0
	s_setprio 1
	v_mfma_f32_16x16x32_bf16 v[112:115], v[156:159], v[182:185], v[112:115]
	v_mfma_f32_16x16x32_bf16 v[104:107], v[172:175], v[182:185], v[104:107]
	v_mfma_f32_16x16x32_bf16 v[96:99], v[156:159], v[190:193], v[96:99]
	v_mfma_f32_16x16x32_bf16 v[88:91], v[172:175], v[190:193], v[88:91]
	v_mfma_f32_16x16x32_bf16 v[80:83], v[156:159], v[198:201], v[80:83]
	v_mfma_f32_16x16x32_bf16 v[72:75], v[172:175], v[198:201], v[72:75]
	v_mfma_f32_16x16x32_bf16 v[68:71], v[156:159], v[206:209], v[68:71]
	v_mfma_f32_16x16x32_bf16 v[64:67], v[172:175], v[206:209], v[64:67]
	v_mfma_f32_16x16x32_bf16 v[112:115], v[168:171], v[186:189], v[112:115]
	v_mfma_f32_16x16x32_bf16 v[104:107], v[178:181], v[186:189], v[104:107]
	v_mfma_f32_16x16x32_bf16 v[96:99], v[168:171], v[194:197], v[96:99]
	v_mfma_f32_16x16x32_bf16 v[88:91], v[178:181], v[194:197], v[88:91]
	v_mfma_f32_16x16x32_bf16 v[80:83], v[168:171], v[202:205], v[80:83]
	v_mfma_f32_16x16x32_bf16 v[72:75], v[178:181], v[202:205], v[72:75]
	v_mfma_f32_16x16x32_bf16 v[68:71], v[168:171], v[210:213], v[68:71]
	v_mfma_f32_16x16x32_bf16 v[64:67], v[178:181], v[210:213], v[64:67]
	s_setprio 0
	s_barrier
; #define PG8_STAGE(bufoff, gbase, voff) do { _Pragma("unroll") for (int _i = 0; _i < 2; ++_i) \
;         __builtin_amdgcn_global_load_lds((const unsigned*)((const char*)(gbase) + (voff)[_i]), (PG8_LAS unsigned*)(lds + (bufoff) + ldsw + _i * 8192), 16, 0, 0); } while (0)
; #define PG8_LDA(dst, b, h) do { _Pragma("unroll") for (int m = 0; m < 4; ++m) _Pragma("unroll") for (int k = 0; k < 2; ++k) dst[m][k] = *(const PG8_LAS bf16x8*)(lds + PG8_SA(b, h) + aoff + m * 2048 + k * 1024); } while (0)
; #define PG8_MMA(ai, bj, At, Bt) do { __builtin_amdgcn_s_setprio(1); _Pragma("unroll") for (int m = 0; m < 4; ++m) _Pragma("unroll") for (int n = 0; n < 2; ++n) _Pragma("unroll") for (int k = 0; k < 2; ++k) \
;         acc[ai][bj][m][n] = __builtin_amdgcn_mfma_f32_16x16x32_bf16(Bt[n][k], At[m][k], acc[ai][bj][m][n], 0, 0, 0); __builtin_amdgcn_s_setprio(0); } while (0)
; #define PG8_WAIT_V(n) asm volatile("s_waitcnt vmcnt(" #n ")" ::: "memory")
; #define PG8_WAIT_L(n) asm volatile("s_waitcnt lgkmcnt(" #n ")" ::: "memory")
; #define PG8_BAR __builtin_amdgcn_s_barrier()
; #define PG8_SCHED __builtin_amdgcn_sched_barrier(0)
; template <class Epi, class Sched, bool ALIGN_EPI = false, bool SP2 = false>
; __device__ __forceinline__ void gemm_phase(PG8_LAS unsigned char* lds, const Gemm g, const Sched& S, const Epi& E) {
;     ...
;             PG8_LDA(At, 1, 1); PG8_STAGE(PG8_SB(1, 0), b3, voffB); PG8_STAGE(PG8_SB(1, 1), b3 + hstep, voffB); PG8_STAGE(PG8_SA(1, 0), a3, voffA);
;             PG8_WAIT_V(8); PG8_WAIT_L(0); PG8_BAR; PG8_MMA(1, 0, At, B0); PG8_MMA(1, 1, At, B1); PG8_BAR; PG8_SCHED;
	s_add_i32 s34, s34, s83
	v_lshl_add_u64 v[150:151], v[150:151], 0, s[22:23]
	s_mov_b32 m0, s34
	ds_read_b128 v[182:185], v155 offset:49152
	ds_read_b128 v[186:189], v155 offset:50176
	ds_read_b128 v[190:193], v155 offset:51200
	ds_read_b128 v[194:197], v155 offset:52224
	ds_read_b128 v[198:201], v155 offset:53248
	ds_read_b128 v[202:205], v155 offset:54272
	ds_read_b128 v[206:209], v155 offset:55296
	ds_read_b128 v[210:213], v155 offset:56320
	global_load_lds_dwordx4 v[150:151], off
	s_add_i32 m0, s34, 0x2000
	s_add_u32 s74, s78, 0x100080
	v_lshl_add_u64 v[150:151], v[214:215], 0, s[22:23]
	s_addc_u32 s75, s79, 0
	s_add_i32 s34, s35, s83
	global_load_lds_dwordx4 v[150:151], off
	v_lshl_add_u64 v[150:151], s[74:75], 0, v[162:163]
	s_mov_b32 m0, s34
	s_nop 0
	global_load_lds_dwordx4 v[150:151], off
	v_lshl_add_u64 v[150:151], s[74:75], 0, v[144:145]
	s_add_i32 m0, s34, 0x2000
	s_nop 0
	global_load_lds_dwordx4 v[150:151], off
	v_lshl_add_u64 v[150:151], v[216:217], 0, s[22:23]
	s_mov_b32 m0, s89
	s_nop 0
	global_load_lds_dwordx4 v[150:151], off
	v_lshl_add_u64 v[150:151], v[224:225], 0, s[22:23]
	s_mov_b32 m0, s90
	s_nop 0
	global_load_lds_dwordx4 v[150:151], off
	s_waitcnt vmcnt(8)
	s_waitcnt lgkmcnt(0)
	s_barrier
	s_setprio 1
	s_waitcnt lgkmcnt(0)
	v_mfma_f32_16x16x32_bf16 v[60:63], v[128:131], v[182:185], v[60:63]
	v_mfma_f32_16x16x32_bf16 v[56:59], v[136:139], v[182:185], v[56:59]
	v_mfma_f32_16x16x32_bf16 v[52:55], v[128:131], v[190:193], v[52:55]
	v_mfma_f32_16x16x32_bf16 v[44:47], v[136:139], v[190:193], v[44:47]
	v_mfma_f32_16x16x32_bf16 v[36:39], v[128:131], v[198:201], v[36:39]
	v_mfma_f32_16x16x32_bf16 v[28:31], v[136:139], v[198:201], v[28:31]
	v_mfma_f32_16x16x32_bf16 v[20:23], v[128:131], v[206:209], v[20:23]
	v_mfma_f32_16x16x32_bf16 v[12:15], v[136:139], v[206:209], v[12:15]
	v_mfma_f32_16x16x32_bf16 v[60:63], v[132:135], v[186:189], v[60:63]
	v_mfma_f32_16x16x32_bf16 v[56:59], v[140:143], v[186:189], v[56:59]
	v_mfma_f32_16x16x32_bf16 v[52:55], v[132:135], v[194:197], v[52:55]
	v_mfma_f32_16x16x32_bf16 v[44:47], v[140:143], v[194:197], v[44:47]
	v_mfma_f32_16x16x32_bf16 v[36:39], v[132:135], v[202:205], v[36:39]
	v_mfma_f32_16x16x32_bf16 v[28:31], v[140:143], v[202:205], v[28:31]
	v_mfma_f32_16x16x32_bf16 v[20:23], v[132:135], v[210:213], v[20:23]
	v_mfma_f32_16x16x32_bf16 v[12:15], v[140:143], v[210:213], v[12:15]
	s_setprio 0
	s_setprio 1
	v_mfma_f32_16x16x32_bf16 v[48:51], v[156:159], v[182:185], v[48:51]
	v_mfma_f32_16x16x32_bf16 v[40:43], v[172:175], v[182:185], v[40:43]
	v_mfma_f32_16x16x32_bf16 v[32:35], v[156:159], v[190:193], v[32:35]
	v_mfma_f32_16x16x32_bf16 v[24:27], v[172:175], v[190:193], v[24:27]
	v_mfma_f32_16x16x32_bf16 v[16:19], v[156:159], v[198:201], v[16:19]
	v_mfma_f32_16x16x32_bf16 v[8:11], v[172:175], v[198:201], v[8:11]
	v_mfma_f32_16x16x32_bf16 v[4:7], v[156:159], v[206:209], v[4:7]
	v_mfma_f32_16x16x32_bf16 v[0:3], v[172:175], v[206:209], v[0:3]
	v_mfma_f32_16x16x32_bf16 v[48:51], v[168:171], v[186:189], v[48:51]
	v_mfma_f32_16x16x32_bf16 v[40:43], v[178:181], v[186:189], v[40:43]
	v_mfma_f32_16x16x32_bf16 v[32:35], v[168:171], v[194:197], v[32:35]
	v_mfma_f32_16x16x32_bf16 v[24:27], v[178:181], v[194:197], v[24:27]
	v_mfma_f32_16x16x32_bf16 v[16:19], v[168:171], v[202:205], v[16:19]
	v_mfma_f32_16x16x32_bf16 v[8:11], v[178:181], v[202:205], v[8:11]
	v_mfma_f32_16x16x32_bf16 v[4:7], v[168:171], v[210:213], v[4:7]
	v_mfma_f32_16x16x32_bf16 v[0:3], v[178:181], v[210:213], v[0:3]
	s_setprio 0
	s_barrier
	s_add_i32 s19, s19, 2
	s_add_u32 s93, s93, 0x100
	s_addc_u32 s94, s94, 0
	s_cmp_gt_u32 s19, 61
	s_mov_b64 s[74:75], s[76:77]
	s_cbranch_scc0 .LBB0_1332
	s_and_b64 vcc, exec, s[6:7]
	s_cbranch_vccz .LBB0_1335
	s_barrier
